# loop-edge edit: K-loop control scalars (counter/pointer bumps, exit compare) issued in the shadow of the last MFMAs instead of after the hand-over barrier
# speedup vs baseline: 1.0119x; 1.0119x over previous
; #define PG8_STAGE(bufoff, gbase, voff) do { _Pragma("unroll") for (int _i = 0; _i < 2; ++_i) \
;         __builtin_amdgcn_global_load_lds((const unsigned*)((const char*)(gbase) + (voff)[_i]), (PG8_LAS unsigned*)(lds + (bufoff) + ldsw + _i * 8192), 16, 0, 0); } while (0)
; #define PG8_LDA(dst, b, h) do { _Pragma("unroll") for (int m = 0; m < 4; ++m) _Pragma("unroll") for (int k = 0; k < 2; ++k) dst[m][k] = *(const PG8_LAS bf16x8*)(lds + PG8_SA(b, h) + aoff + m * 2048 + k * 1024); } while (0)
; #define PG8_LDB(dst, b, h) do { _Pragma("unroll") for (int n = 0; n < 2; ++n) _Pragma("unroll") for (int k = 0; k < 2; ++k) dst[n][k] = *(const PG8_LAS bf16x8*)(lds + PG8_SB(b, h) + boff + n * 2048 + k * 1024); } while (0)
; #define PG8_MMA(ai, bj, At, Bt) do { __builtin_amdgcn_s_setprio(1); _Pragma("unroll") for (int m = 0; m < 4; ++m) _Pragma("unroll") for (int n = 0; n < 2; ++n) _Pragma("unroll") for (int k = 0; k < 2; ++k) \
;         acc[ai][bj][m][n] = __builtin_amdgcn_mfma_f32_16x16x32_bf16(Bt[n][k], At[m][k], acc[ai][bj][m][n], 0, 0, 0); __builtin_amdgcn_s_setprio(0); } while (0)
; #define PG8_BAR __builtin_amdgcn_s_barrier()
; template <class Epi, class Sched, bool ALIGN_EPI = false, bool SP2 = false>
; __device__ __forceinline__ void gemm_phase(PG8_LAS unsigned char* lds, const Gemm g, const Sched S, const Epi E) {
;     ...
;         for (int t = 0; t < nt; t += 2) {
;             if constexpr (Epi::MIDT >= 0) { if (t == Epi::MIDT) E.mid(acc, cur, wr, fr); }
;             const bool last = (t == nt - 2);
;             const char* a1 = cA + (size_t)(t + 1) * kstep;
;             const char* a2 = last ? nA : cA + (size_t)(t + 2) * kstep; const char* b2 = last ? nB : cB + (size_t)(t + 2) * kstep;
;             const char* a3 = a2 + kstep; const char* b3 = b2 + kstep;
;             if (last && has_next) S.a_ready(nxt);
;             if constexpr (SP2) {
;             PG8_LDB(B0, 0, 0); PG8_LDB(B1, 0, 1); PG8_SCHED; PG8_LDA(At, 0, 0); PG8_STAGE(PG8_SA(1, 1), a1 + hstep, voffA);
;             PG8_WAIT_V(8); PG8_WAIT_L(0); PG8_BAR; PG8_MMA(0, 0, At, B0); PG8_MMA(0, 1, At, B1); PG8_BAR; PG8_SCHED;
;             PG8_LDA(At, 0, 1); PG8_STAGE(PG8_SB(0, 0), b2, voffB); PG8_STAGE(PG8_SB(0, 1), b2 + hstep, voffB); PG8_STAGE(PG8_SA(0, 0), a2, voffA);
;             PG8_WAIT_V(8); PG8_WAIT_L(0); PG8_BAR; PG8_MMA(1, 0, At, B0); PG8_MMA(1, 1, At, B1); PG8_BAR; PG8_SCHED;
.Lpagefit_1:
.LBB0_276:
	ds_read_b128 v[152:155], v149
	ds_read_b128 v[156:159], v149 offset:1024
	ds_read_b128 v[160:163], v149 offset:2048
	ds_read_b128 v[164:167], v149 offset:3072
	ds_read_b128 v[168:171], v150
	ds_read_b128 v[172:175], v150 offset:1024
	ds_read_b128 v[176:179], v150 offset:2048
	ds_read_b128 v[180:183], v150 offset:3072
	s_add_u32 s44, s42, 0xfffc0080
	s_addc_u32 s45, s43, -1
	s_cmp_eq_u32 s69, 12
	s_cselect_b32 s51, s19, s45
	s_cselect_b32 s50, s63, s44
	s_cselect_b32 s45, s17, s68
	s_cselect_b32 s44, s64, s65
	v_lshl_add_u64 v[144:145], s[42:43], 0, v[136:137]
	s_add_i32 m0, s33, 0xc000
	ds_read_b128 v[190:193], v151
	ds_read_b128 v[194:197], v151 offset:1024
	ds_read_b128 v[198:201], v151 offset:2048
	ds_read_b128 v[202:205], v151 offset:3072
	ds_read_b128 v[206:209], v151 offset:4096
	ds_read_b128 v[210:213], v151 offset:5120
	ds_read_b128 v[214:217], v151 offset:6144
	ds_read_b128 v[218:221], v151 offset:7168
	global_load_lds_dwordx4 v[144:145], off
	v_lshl_add_u64 v[144:145], s[42:43], 0, v[138:139]
	s_add_i32 m0, s33, 0xe000
	s_nop 0
	global_load_lds_dwordx4 v[144:145], off
	s_waitcnt vmcnt(8)
	s_waitcnt lgkmcnt(0)
	s_barrier
	s_setprio 1
	s_waitcnt lgkmcnt(0)
	v_mfma_f32_16x16x32_bf16 v[124:127], v[152:155], v[190:193], v[124:127]
	v_mfma_f32_16x16x32_bf16 v[116:119], v[160:163], v[190:193], v[116:119]
	v_mfma_f32_16x16x32_bf16 v[108:111], v[152:155], v[198:201], v[108:111]
	v_mfma_f32_16x16x32_bf16 v[100:103], v[160:163], v[198:201], v[100:103]
	v_mfma_f32_16x16x32_bf16 v[92:95], v[152:155], v[206:209], v[92:95]
	v_mfma_f32_16x16x32_bf16 v[84:87], v[160:163], v[206:209], v[84:87]
	v_mfma_f32_16x16x32_bf16 v[76:79], v[152:155], v[214:217], v[76:79]
	v_mfma_f32_16x16x32_bf16 v[68:71], v[160:163], v[214:217], v[68:71]
	v_mfma_f32_16x16x32_bf16 v[124:127], v[156:159], v[194:197], v[124:127]
	v_mfma_f32_16x16x32_bf16 v[116:119], v[164:167], v[194:197], v[116:119]
	v_mfma_f32_16x16x32_bf16 v[108:111], v[156:159], v[202:205], v[108:111]
	v_mfma_f32_16x16x32_bf16 v[100:103], v[164:167], v[202:205], v[100:103]
	v_mfma_f32_16x16x32_bf16 v[92:95], v[156:159], v[210:213], v[92:95]
	v_mfma_f32_16x16x32_bf16 v[84:87], v[164:167], v[210:213], v[84:87]
	v_mfma_f32_16x16x32_bf16 v[76:79], v[156:159], v[218:221], v[76:79]
	v_mfma_f32_16x16x32_bf16 v[68:71], v[164:167], v[218:221], v[68:71]
	s_setprio 0
	s_setprio 1
	v_mfma_f32_16x16x32_bf16 v[120:123], v[168:171], v[190:193], v[120:123]
	v_mfma_f32_16x16x32_bf16 v[112:115], v[176:179], v[190:193], v[112:115]
	v_mfma_f32_16x16x32_bf16 v[104:107], v[168:171], v[198:201], v[104:107]
	v_mfma_f32_16x16x32_bf16 v[96:99], v[176:179], v[198:201], v[96:99]
	v_mfma_f32_16x16x32_bf16 v[88:91], v[168:171], v[206:209], v[88:91]
	v_mfma_f32_16x16x32_bf16 v[80:83], v[176:179], v[206:209], v[80:83]
	v_mfma_f32_16x16x32_bf16 v[72:75], v[168:171], v[214:217], v[72:75]
	v_mfma_f32_16x16x32_bf16 v[64:67], v[176:179], v[214:217], v[64:67]
	v_mfma_f32_16x16x32_bf16 v[120:123], v[172:175], v[194:197], v[120:123]
	v_mfma_f32_16x16x32_bf16 v[112:115], v[180:183], v[194:197], v[112:115]
	v_mfma_f32_16x16x32_bf16 v[104:107], v[172:175], v[202:205], v[104:107]
	v_mfma_f32_16x16x32_bf16 v[96:99], v[180:183], v[202:205], v[96:99]
	v_mfma_f32_16x16x32_bf16 v[88:91], v[172:175], v[210:213], v[88:91]
	v_mfma_f32_16x16x32_bf16 v[80:83], v[180:183], v[210:213], v[80:83]
	v_mfma_f32_16x16x32_bf16 v[72:75], v[172:175], v[218:221], v[72:75]
	v_mfma_f32_16x16x32_bf16 v[64:67], v[180:183], v[218:221], v[64:67]
	s_setprio 0
	s_barrier
	s_add_i32 s82, s59, s8
	v_lshl_add_u64 v[144:145], s[44:45], 0, v[132:133]
	s_mov_b32 m0, s82
	ds_read_b128 v[190:193], v151 offset:16384
	ds_read_b128 v[194:197], v151 offset:17408
	ds_read_b128 v[198:201], v151 offset:18432
	ds_read_b128 v[202:205], v151 offset:19456
	ds_read_b128 v[206:209], v151 offset:20480
	ds_read_b128 v[210:213], v151 offset:21504
	ds_read_b128 v[214:217], v151 offset:22528
	ds_read_b128 v[218:221], v151 offset:23552
	global_load_lds_dwordx4 v[144:145], off
	s_add_i32 m0, s82, 0x2000
	s_add_u32 s82, s44, 0x40000
	v_lshl_add_u64 v[184:185], s[44:45], 0, v[128:129]
	s_addc_u32 s83, s45, 0
	s_add_i32 s84, s60, s8
	global_load_lds_dwordx4 v[184:185], off
	v_lshl_add_u64 v[222:223], s[82:83], 0, v[132:133]
	s_mov_b32 m0, s84
	v_lshl_add_u64 v[224:225], s[50:51], 0, v[130:131]
	global_load_lds_dwordx4 v[222:223], off
	v_lshl_add_u64 v[222:223], s[82:83], 0, v[128:129]
	s_add_i32 m0, s84, 0x2000
	s_nop 0
	global_load_lds_dwordx4 v[222:223], off
	v_lshl_add_u64 v[222:223], s[50:51], 0, v[134:135]
	s_mov_b32 m0, s33
	s_nop 0
	global_load_lds_dwordx4 v[222:223], off
	s_mov_b32 m0, s36
	s_nop 0
	global_load_lds_dwordx4 v[224:225], off
	s_waitcnt vmcnt(8)
	s_waitcnt lgkmcnt(0)
	s_barrier
; #define PG8_STAGE(bufoff, gbase, voff) do { _Pragma("unroll") for (int _i = 0; _i < 2; ++_i) \
;         __builtin_amdgcn_global_load_lds((const unsigned*)((const char*)(gbase) + (voff)[_i]), (PG8_LAS unsigned*)(lds + (bufoff) + ldsw + _i * 8192), 16, 0, 0); } while (0)
; #define PG8_LDA(dst, b, h) do { _Pragma("unroll") for (int m = 0; m < 4; ++m) _Pragma("unroll") for (int k = 0; k < 2; ++k) dst[m][k] = *(const PG8_LAS bf16x8*)(lds + PG8_SA(b, h) + aoff + m * 2048 + k * 1024); } while (0)
; #define PG8_LDB(dst, b, h) do { _Pragma("unroll") for (int n = 0; n < 2; ++n) _Pragma("unroll") for (int k = 0; k < 2; ++k) dst[n][k] = *(const PG8_LAS bf16x8*)(lds + PG8_SB(b, h) + boff + n * 2048 + k * 1024); } while (0)
; #define PG8_MMA(ai, bj, At, Bt) do { __builtin_amdgcn_s_setprio(1); _Pragma("unroll") for (int m = 0; m < 4; ++m) _Pragma("unroll") for (int n = 0; n < 2; ++n) _Pragma("unroll") for (int k = 0; k < 2; ++k) \
;         acc[ai][bj][m][n] = __builtin_amdgcn_mfma_f32_16x16x32_bf16(Bt[n][k], At[m][k], acc[ai][bj][m][n], 0, 0, 0); __builtin_amdgcn_s_setprio(0); } while (0)
; #define PG8_WAIT_V(n) asm volatile("s_waitcnt vmcnt(" #n ")" ::: "memory")
; #define PG8_WAIT_L(n) asm volatile("s_waitcnt lgkmcnt(" #n ")" ::: "memory")
; #define PG8_BAR __builtin_amdgcn_s_barrier()
; #define PG8_SCHED __builtin_amdgcn_sched_barrier(0)
; template <class Epi, class Sched, bool ALIGN_EPI = false, bool SP2 = false>
; __device__ __forceinline__ void gemm_phase(PG8_LAS unsigned char* lds, const Gemm g, const Sched S, const Epi E) {
;     ...
;             PG8_WAIT_V(8); PG8_WAIT_L(0); PG8_BAR; PG8_MMA(1, 0, At, B0); PG8_MMA(1, 1, At, B1); PG8_BAR; PG8_SCHED;
;             PG8_LDB(B0, 1, 0); PG8_LDB(B1, 1, 1); PG8_SCHED; PG8_LDA(At, 1, 0); PG8_STAGE(PG8_SA(0, 1), a2 + hstep, voffA);
;             PG8_WAIT_V(8); PG8_WAIT_L(0); PG8_BAR; PG8_MMA(0, 0, At, B0); PG8_MMA(0, 1, At, B1); PG8_BAR; PG8_SCHED;
	s_setprio 1
	s_waitcnt lgkmcnt(0)
	v_mfma_f32_16x16x32_bf16 v[60:63], v[152:155], v[190:193], v[60:63]
	v_mfma_f32_16x16x32_bf16 v[52:55], v[160:163], v[190:193], v[52:55]
	v_mfma_f32_16x16x32_bf16 v[44:47], v[152:155], v[198:201], v[44:47]
	v_mfma_f32_16x16x32_bf16 v[36:39], v[160:163], v[198:201], v[36:39]
	v_mfma_f32_16x16x32_bf16 v[28:31], v[152:155], v[206:209], v[28:31]
	v_mfma_f32_16x16x32_bf16 v[20:23], v[160:163], v[206:209], v[20:23]
	v_mfma_f32_16x16x32_bf16 v[12:15], v[152:155], v[214:217], v[12:15]
	v_mfma_f32_16x16x32_bf16 v[4:7], v[160:163], v[214:217], v[4:7]
	v_mfma_f32_16x16x32_bf16 v[60:63], v[156:159], v[194:197], v[60:63]
	v_mfma_f32_16x16x32_bf16 v[52:55], v[164:167], v[194:197], v[52:55]
	v_mfma_f32_16x16x32_bf16 v[44:47], v[156:159], v[202:205], v[44:47]
	v_mfma_f32_16x16x32_bf16 v[36:39], v[164:167], v[202:205], v[36:39]
	v_mfma_f32_16x16x32_bf16 v[28:31], v[156:159], v[210:213], v[28:31]
	v_mfma_f32_16x16x32_bf16 v[20:23], v[164:167], v[210:213], v[20:23]
	v_mfma_f32_16x16x32_bf16 v[12:15], v[156:159], v[218:221], v[12:15]
	v_mfma_f32_16x16x32_bf16 v[4:7], v[164:167], v[218:221], v[4:7]
	s_setprio 0
	s_setprio 1
	v_mfma_f32_16x16x32_bf16 v[56:59], v[168:171], v[190:193], v[56:59]
	v_mfma_f32_16x16x32_bf16 v[48:51], v[176:179], v[190:193], v[48:51]
	v_mfma_f32_16x16x32_bf16 v[40:43], v[168:171], v[198:201], v[40:43]
	v_mfma_f32_16x16x32_bf16 v[32:35], v[176:179], v[198:201], v[32:35]
	v_mfma_f32_16x16x32_bf16 v[24:27], v[168:171], v[206:209], v[24:27]
	v_mfma_f32_16x16x32_bf16 v[16:19], v[176:179], v[206:209], v[16:19]
	v_mfma_f32_16x16x32_bf16 v[8:11], v[168:171], v[214:217], v[8:11]
	v_mfma_f32_16x16x32_bf16 v[0:3], v[176:179], v[214:217], v[0:3]
	v_mfma_f32_16x16x32_bf16 v[56:59], v[172:175], v[194:197], v[56:59]
	v_mfma_f32_16x16x32_bf16 v[48:51], v[180:183], v[194:197], v[48:51]
	v_mfma_f32_16x16x32_bf16 v[40:43], v[172:175], v[202:205], v[40:43]
	v_mfma_f32_16x16x32_bf16 v[32:35], v[180:183], v[202:205], v[32:35]
	v_mfma_f32_16x16x32_bf16 v[24:27], v[172:175], v[210:213], v[24:27]
	v_mfma_f32_16x16x32_bf16 v[16:19], v[180:183], v[210:213], v[16:19]
	v_mfma_f32_16x16x32_bf16 v[8:11], v[172:175], v[218:221], v[8:11]
	v_mfma_f32_16x16x32_bf16 v[0:3], v[180:183], v[218:221], v[0:3]
	s_setprio 0
	s_barrier
	s_add_i32 s82, 0, 0x18000
	s_add_i32 s83, 0, 0x1c000
	v_add_u32_e32 v164, s82, v148
	v_add_u32_e32 v180, s83, v148
	ds_read_b128 v[152:155], v164
	ds_read_b128 v[156:159], v164 offset:1024
	ds_read_b128 v[160:163], v164 offset:2048
	ds_read_b128 v[164:167], v164 offset:3072
	ds_read_b128 v[168:171], v180
	ds_read_b128 v[172:175], v180 offset:1024
	ds_read_b128 v[176:179], v180 offset:2048
	ds_read_b128 v[180:183], v180 offset:3072
	s_add_u32 s50, s50, 0x40000
	s_addc_u32 s51, s51, 0
	s_mov_b32 m0, s37
	v_lshl_add_u64 v[226:227], s[50:51], 0, v[134:135]
	ds_read_b128 v[190:193], v151 offset:32768
	ds_read_b128 v[194:197], v151 offset:33792
	ds_read_b128 v[198:201], v151 offset:34816
	ds_read_b128 v[202:205], v151 offset:35840
	ds_read_b128 v[206:209], v151 offset:36864
	ds_read_b128 v[210:213], v151 offset:37888
	ds_read_b128 v[214:217], v151 offset:38912
	ds_read_b128 v[218:221], v151 offset:39936
	global_load_lds_dwordx4 v[226:227], off
	v_lshl_add_u64 v[226:227], s[50:51], 0, v[130:131]
	s_mov_b32 m0, s41
	s_nop 0
	global_load_lds_dwordx4 v[226:227], off
	s_waitcnt vmcnt(8)
	s_waitcnt lgkmcnt(0)
	s_barrier
	s_setprio 1
	s_waitcnt lgkmcnt(0)
	v_mfma_f32_16x16x32_bf16 v[124:127], v[152:155], v[190:193], v[124:127]
	v_mfma_f32_16x16x32_bf16 v[116:119], v[160:163], v[190:193], v[116:119]
	v_mfma_f32_16x16x32_bf16 v[108:111], v[152:155], v[198:201], v[108:111]
	v_mfma_f32_16x16x32_bf16 v[100:103], v[160:163], v[198:201], v[100:103]
	v_mfma_f32_16x16x32_bf16 v[92:95], v[152:155], v[206:209], v[92:95]
	v_mfma_f32_16x16x32_bf16 v[84:87], v[160:163], v[206:209], v[84:87]
	v_mfma_f32_16x16x32_bf16 v[76:79], v[152:155], v[214:217], v[76:79]
	v_mfma_f32_16x16x32_bf16 v[68:71], v[160:163], v[214:217], v[68:71]
	v_mfma_f32_16x16x32_bf16 v[124:127], v[156:159], v[194:197], v[124:127]
	v_mfma_f32_16x16x32_bf16 v[116:119], v[164:167], v[194:197], v[116:119]
	v_mfma_f32_16x16x32_bf16 v[108:111], v[156:159], v[202:205], v[108:111]
	v_mfma_f32_16x16x32_bf16 v[100:103], v[164:167], v[202:205], v[100:103]
	v_mfma_f32_16x16x32_bf16 v[92:95], v[156:159], v[210:213], v[92:95]
	v_mfma_f32_16x16x32_bf16 v[84:87], v[164:167], v[210:213], v[84:87]
	v_mfma_f32_16x16x32_bf16 v[76:79], v[156:159], v[218:221], v[76:79]
	v_mfma_f32_16x16x32_bf16 v[68:71], v[164:167], v[218:221], v[68:71]
	s_setprio 0
	s_setprio 1
	v_mfma_f32_16x16x32_bf16 v[120:123], v[168:171], v[190:193], v[120:123]
	v_mfma_f32_16x16x32_bf16 v[112:115], v[176:179], v[190:193], v[112:115]
	v_mfma_f32_16x16x32_bf16 v[104:107], v[168:171], v[198:201], v[104:107]
	v_mfma_f32_16x16x32_bf16 v[96:99], v[176:179], v[198:201], v[96:99]
	v_mfma_f32_16x16x32_bf16 v[88:91], v[168:171], v[206:209], v[88:91]
	v_mfma_f32_16x16x32_bf16 v[80:83], v[176:179], v[206:209], v[80:83]
	v_mfma_f32_16x16x32_bf16 v[72:75], v[168:171], v[214:217], v[72:75]
	v_mfma_f32_16x16x32_bf16 v[64:67], v[176:179], v[214:217], v[64:67]
	v_mfma_f32_16x16x32_bf16 v[120:123], v[172:175], v[194:197], v[120:123]
	v_mfma_f32_16x16x32_bf16 v[112:115], v[180:183], v[194:197], v[112:115]
	v_mfma_f32_16x16x32_bf16 v[104:107], v[172:175], v[202:205], v[104:107]
	v_mfma_f32_16x16x32_bf16 v[96:99], v[180:183], v[202:205], v[96:99]
	v_mfma_f32_16x16x32_bf16 v[88:91], v[172:175], v[210:213], v[88:91]
	v_mfma_f32_16x16x32_bf16 v[80:83], v[180:183], v[210:213], v[80:83]
	v_mfma_f32_16x16x32_bf16 v[72:75], v[172:175], v[218:221], v[72:75]
	v_mfma_f32_16x16x32_bf16 v[64:67], v[180:183], v[218:221], v[64:67]
	s_setprio 0
	s_barrier
; #define PG8_STAGE(bufoff, gbase, voff) do { _Pragma("unroll") for (int _i = 0; _i < 2; ++_i) \
;         __builtin_amdgcn_global_load_lds((const unsigned*)((const char*)(gbase) + (voff)[_i]), (PG8_LAS unsigned*)(lds + (bufoff) + ldsw + _i * 8192), 16, 0, 0); } while (0)
; #define PG8_LDA(dst, b, h) do { _Pragma("unroll") for (int m = 0; m < 4; ++m) _Pragma("unroll") for (int k = 0; k < 2; ++k) dst[m][k] = *(const PG8_LAS bf16x8*)(lds + PG8_SA(b, h) + aoff + m * 2048 + k * 1024); } while (0)
; #define PG8_MMA(ai, bj, At, Bt) do { __builtin_amdgcn_s_setprio(1); _Pragma("unroll") for (int m = 0; m < 4; ++m) _Pragma("unroll") for (int n = 0; n < 2; ++n) _Pragma("unroll") for (int k = 0; k < 2; ++k) \
;         acc[ai][bj][m][n] = __builtin_amdgcn_mfma_f32_16x16x32_bf16(Bt[n][k], At[m][k], acc[ai][bj][m][n], 0, 0, 0); __builtin_amdgcn_s_setprio(0); } while (0)
; #define PG8_WAIT_V(n) asm volatile("s_waitcnt vmcnt(" #n ")" ::: "memory")
; #define PG8_WAIT_L(n) asm volatile("s_waitcnt lgkmcnt(" #n ")" ::: "memory")
; #define PG8_BAR __builtin_amdgcn_s_barrier()
; #define PG8_SCHED __builtin_amdgcn_sched_barrier(0)
; template <class Epi, class Sched, bool ALIGN_EPI = false, bool SP2 = false>
; __device__ __forceinline__ void gemm_phase(PG8_LAS unsigned char* lds, const Gemm g, const Sched S, const Epi E) {
;     ...
;         for (int t = 0; t < nt; t += 2) {
;             if constexpr (Epi::MIDT >= 0) { if (t == Epi::MIDT) E.mid(acc, cur, wr, fr); }
;             const bool last = (t == nt - 2);
;             const char* a1 = cA + (size_t)(t + 1) * kstep;
;             const char* a2 = last ? nA : cA + (size_t)(t + 2) * kstep; const char* b2 = last ? nB : cB + (size_t)(t + 2) * kstep;
;             const char* a3 = a2 + kstep; const char* b3 = b2 + kstep;
;     ...
;             PG8_LDA(At, 1, 1); PG8_STAGE(PG8_SB(1, 0), b3, voffB); PG8_STAGE(PG8_SB(1, 1), b3 + hstep, voffB); PG8_STAGE(PG8_SA(1, 0), a3, voffA);
;             PG8_WAIT_V(8); PG8_WAIT_L(0); PG8_BAR; PG8_MMA(1, 0, At, B0); PG8_MMA(1, 1, At, B1); PG8_BAR; PG8_SCHED;
	s_add_i32 s50, s82, s8
	v_lshl_add_u64 v[144:145], v[144:145], 0, s[12:13]
	s_mov_b32 m0, s50
	ds_read_b128 v[190:193], v151 offset:49152
	ds_read_b128 v[194:197], v151 offset:50176
	ds_read_b128 v[198:201], v151 offset:51200
	ds_read_b128 v[202:205], v151 offset:52224
	ds_read_b128 v[206:209], v151 offset:53248
	ds_read_b128 v[210:213], v151 offset:54272
	ds_read_b128 v[214:217], v151 offset:55296
	ds_read_b128 v[218:221], v151 offset:56320
	global_load_lds_dwordx4 v[144:145], off
	s_add_i32 m0, s50, 0x2000
	s_add_u32 s44, s44, 0x40080
	v_lshl_add_u64 v[144:145], v[184:185], 0, s[12:13]
	s_addc_u32 s45, s45, 0
	s_add_i32 s50, s83, s8
	global_load_lds_dwordx4 v[144:145], off
	v_lshl_add_u64 v[144:145], s[44:45], 0, v[132:133]
	s_mov_b32 m0, s50
	s_nop 0
	global_load_lds_dwordx4 v[144:145], off
	v_lshl_add_u64 v[144:145], s[44:45], 0, v[128:129]
	s_add_i32 m0, s50, 0x2000
	s_nop 0
	global_load_lds_dwordx4 v[144:145], off
	v_lshl_add_u64 v[144:145], v[222:223], 0, s[12:13]
	s_mov_b32 m0, s49
	s_nop 0
	global_load_lds_dwordx4 v[144:145], off
	v_lshl_add_u64 v[144:145], v[224:225], 0, s[12:13]
	s_mov_b32 m0, s54
	s_nop 0
	global_load_lds_dwordx4 v[144:145], off
	s_waitcnt vmcnt(8)
	s_waitcnt lgkmcnt(0)
	s_barrier
	s_setprio 1
	s_waitcnt lgkmcnt(0)
	v_mfma_f32_16x16x32_bf16 v[60:63], v[152:155], v[190:193], v[60:63]
	v_mfma_f32_16x16x32_bf16 v[52:55], v[160:163], v[190:193], v[52:55]
	v_mfma_f32_16x16x32_bf16 v[44:47], v[152:155], v[198:201], v[44:47]
	v_mfma_f32_16x16x32_bf16 v[36:39], v[160:163], v[198:201], v[36:39]
	v_mfma_f32_16x16x32_bf16 v[28:31], v[152:155], v[206:209], v[28:31]
	v_mfma_f32_16x16x32_bf16 v[20:23], v[160:163], v[206:209], v[20:23]
	v_mfma_f32_16x16x32_bf16 v[12:15], v[152:155], v[214:217], v[12:15]
	v_mfma_f32_16x16x32_bf16 v[4:7], v[160:163], v[214:217], v[4:7]
	v_mfma_f32_16x16x32_bf16 v[60:63], v[156:159], v[194:197], v[60:63]
	v_mfma_f32_16x16x32_bf16 v[52:55], v[164:167], v[194:197], v[52:55]
	v_mfma_f32_16x16x32_bf16 v[44:47], v[156:159], v[202:205], v[44:47]
	v_mfma_f32_16x16x32_bf16 v[36:39], v[164:167], v[202:205], v[36:39]
	v_mfma_f32_16x16x32_bf16 v[28:31], v[156:159], v[210:213], v[28:31]
	v_mfma_f32_16x16x32_bf16 v[20:23], v[164:167], v[210:213], v[20:23]
	v_mfma_f32_16x16x32_bf16 v[12:15], v[156:159], v[218:221], v[12:15]
	v_mfma_f32_16x16x32_bf16 v[4:7], v[164:167], v[218:221], v[4:7]
	s_setprio 0
	s_setprio 1
	v_mfma_f32_16x16x32_bf16 v[56:59], v[168:171], v[190:193], v[56:59]
	v_mfma_f32_16x16x32_bf16 v[48:51], v[176:179], v[190:193], v[48:51]
	v_mfma_f32_16x16x32_bf16 v[40:43], v[168:171], v[198:201], v[40:43]
	v_mfma_f32_16x16x32_bf16 v[32:35], v[176:179], v[198:201], v[32:35]
	v_mfma_f32_16x16x32_bf16 v[24:27], v[168:171], v[206:209], v[24:27]
	v_mfma_f32_16x16x32_bf16 v[16:19], v[176:179], v[206:209], v[16:19]
	v_mfma_f32_16x16x32_bf16 v[8:11], v[168:171], v[214:217], v[8:11]
	v_mfma_f32_16x16x32_bf16 v[0:3], v[176:179], v[214:217], v[0:3]
	v_mfma_f32_16x16x32_bf16 v[56:59], v[172:175], v[194:197], v[56:59]
	v_mfma_f32_16x16x32_bf16 v[48:51], v[180:183], v[194:197], v[48:51]
	v_mfma_f32_16x16x32_bf16 v[40:43], v[172:175], v[202:205], v[40:43]
	v_mfma_f32_16x16x32_bf16 v[32:35], v[180:183], v[202:205], v[32:35]
	s_add_i32 s69, s69, 2
	s_add_u32 s42, s42, 0x100
	s_addc_u32 s43, s43, 0
	s_add_u32 s65, s65, 0x100
	s_addc_u32 s68, s68, 0
	s_cmp_gt_u32 s69, 13
	v_mfma_f32_16x16x32_bf16 v[24:27], v[172:175], v[210:213], v[24:27]
	v_mfma_f32_16x16x32_bf16 v[16:19], v[180:183], v[210:213], v[16:19]
	v_mfma_f32_16x16x32_bf16 v[8:11], v[172:175], v[218:221], v[8:11]
	v_mfma_f32_16x16x32_bf16 v[0:3], v[180:183], v[218:221], v[0:3]
	s_setprio 0
	s_barrier
	s_cbranch_scc0 .LBB0_276
	s_and_b64 vcc, exec, s[14:15]
	s_cbranch_vccz .LBB0_279
	s_barrier

; #define PG8_STAGE(bufoff, gbase, voff) do { _Pragma("unroll") for (int _i = 0; _i < 2; ++_i) \
;         __builtin_amdgcn_global_load_lds((const unsigned*)((const char*)(gbase) + (voff)[_i]), (PG8_LAS unsigned*)(lds + (bufoff) + ldsw + _i * 8192), 16, 0, 0); } while (0)
; #define PG8_LDA(dst, b, h) do { _Pragma("unroll") for (int m = 0; m < 4; ++m) _Pragma("unroll") for (int k = 0; k < 2; ++k) dst[m][k] = *(const PG8_LAS bf16x8*)(lds + PG8_SA(b, h) + aoff + m * 2048 + k * 1024); } while (0)
; #define PG8_LDB(dst, b, h) do { _Pragma("unroll") for (int n = 0; n < 2; ++n) _Pragma("unroll") for (int k = 0; k < 2; ++k) dst[n][k] = *(const PG8_LAS bf16x8*)(lds + PG8_SB(b, h) + boff + n * 2048 + k * 1024); } while (0)
; #define PG8_MMA(ai, bj, At, Bt) do { __builtin_amdgcn_s_setprio(1); _Pragma("unroll") for (int m = 0; m < 4; ++m) _Pragma("unroll") for (int n = 0; n < 2; ++n) _Pragma("unroll") for (int k = 0; k < 2; ++k) \
;         acc[ai][bj][m][n] = __builtin_amdgcn_mfma_f32_16x16x32_bf16(Bt[n][k], At[m][k], acc[ai][bj][m][n], 0, 0, 0); __builtin_amdgcn_s_setprio(0); } while (0)
; #define PG8_BAR __builtin_amdgcn_s_barrier()
; template <class Epi, class Sched, bool ALIGN_EPI = false, bool SP2 = false>
; __device__ __forceinline__ void gemm_phase(PG8_LAS unsigned char* lds, const Gemm g, const Sched S, const Epi E) {
;     ...
;         for (int t = 0; t < nt; t += 2) {
;             if constexpr (Epi::MIDT >= 0) { if (t == Epi::MIDT) E.mid(acc, cur, wr, fr); }
;             const bool last = (t == nt - 2);
;             const char* a1 = cA + (size_t)(t + 1) * kstep;
;             const char* a2 = last ? nA : cA + (size_t)(t + 2) * kstep; const char* b2 = last ? nB : cB + (size_t)(t + 2) * kstep;
;             const char* a3 = a2 + kstep; const char* b3 = b2 + kstep;
;             if (last && has_next) S.a_ready(nxt);
;             if constexpr (SP2) {
;             PG8_LDB(B0, 0, 0); PG8_LDB(B1, 0, 1); PG8_SCHED; PG8_LDA(At, 0, 0); PG8_STAGE(PG8_SA(1, 1), a1 + hstep, voffA);
;             PG8_WAIT_V(8); PG8_WAIT_L(0); PG8_BAR; PG8_MMA(0, 0, At, B0); PG8_MMA(0, 1, At, B1); PG8_BAR; PG8_SCHED;
;             PG8_LDA(At, 0, 1); PG8_STAGE(PG8_SB(0, 0), b2, voffB); PG8_STAGE(PG8_SB(0, 1), b2 + hstep, voffB); PG8_STAGE(PG8_SA(0, 0), a2, voffA);
;             PG8_WAIT_V(8); PG8_WAIT_L(0); PG8_BAR; PG8_MMA(1, 0, At, B0); PG8_MMA(1, 1, At, B1); PG8_BAR; PG8_SCHED;
.LBB0_356:
	ds_read_b128 v[144:147], v157
	ds_read_b128 v[148:151], v157 offset:1024
	ds_read_b128 v[160:163], v157 offset:2048
	ds_read_b128 v[164:167], v157 offset:3072
	ds_read_b128 v[168:171], v158
	ds_read_b128 v[172:175], v158 offset:1024
	ds_read_b128 v[176:179], v158 offset:2048
	ds_read_b128 v[180:183], v158 offset:3072
	s_add_u32 s40, s38, 0x100
	s_addc_u32 s41, s39, 0
	s_cmp_eq_u32 s65, 40
	s_cselect_b32 s45, s5, s41
	s_cselect_b32 s44, s4, s40
	s_cselect_b32 s43, s17, s64
	s_cselect_b32 s42, s16, s63
	v_lshl_add_u64 v[152:153], s[38:39], 0, v[136:137]
	s_add_i32 m0, s9, 0xc000
	ds_read_b128 v[190:193], v159
	ds_read_b128 v[194:197], v159 offset:1024
	ds_read_b128 v[198:201], v159 offset:2048
	ds_read_b128 v[202:205], v159 offset:3072
	ds_read_b128 v[206:209], v159 offset:4096
	ds_read_b128 v[210:213], v159 offset:5120
	ds_read_b128 v[214:217], v159 offset:6144
	ds_read_b128 v[218:221], v159 offset:7168
	global_load_lds_dwordx4 v[152:153], off
	v_lshl_add_u64 v[152:153], s[38:39], 0, v[138:139]
	s_add_i32 m0, s9, 0xe000
	s_nop 0
	global_load_lds_dwordx4 v[152:153], off
	s_waitcnt vmcnt(8)
	s_waitcnt lgkmcnt(0)
	s_barrier
	s_setprio 1
	s_waitcnt lgkmcnt(0)
	v_mfma_f32_16x16x32_bf16 v[124:127], v[144:147], v[190:193], v[124:127]
	v_mfma_f32_16x16x32_bf16 v[120:123], v[160:163], v[190:193], v[120:123]
	v_mfma_f32_16x16x32_bf16 v[108:111], v[144:147], v[198:201], v[108:111]
	v_mfma_f32_16x16x32_bf16 v[104:107], v[160:163], v[198:201], v[104:107]
	v_mfma_f32_16x16x32_bf16 v[92:95], v[144:147], v[206:209], v[92:95]
	v_mfma_f32_16x16x32_bf16 v[88:91], v[160:163], v[206:209], v[88:91]
	v_mfma_f32_16x16x32_bf16 v[76:79], v[144:147], v[214:217], v[76:79]
	v_mfma_f32_16x16x32_bf16 v[72:75], v[160:163], v[214:217], v[72:75]
	v_mfma_f32_16x16x32_bf16 v[124:127], v[148:151], v[194:197], v[124:127]
	v_mfma_f32_16x16x32_bf16 v[120:123], v[164:167], v[194:197], v[120:123]
	v_mfma_f32_16x16x32_bf16 v[108:111], v[148:151], v[202:205], v[108:111]
	v_mfma_f32_16x16x32_bf16 v[104:107], v[164:167], v[202:205], v[104:107]
	v_mfma_f32_16x16x32_bf16 v[92:95], v[148:151], v[210:213], v[92:95]
	v_mfma_f32_16x16x32_bf16 v[88:91], v[164:167], v[210:213], v[88:91]
	v_mfma_f32_16x16x32_bf16 v[76:79], v[148:151], v[218:221], v[76:79]
	v_mfma_f32_16x16x32_bf16 v[72:75], v[164:167], v[218:221], v[72:75]
	s_setprio 0
	s_setprio 1
	v_mfma_f32_16x16x32_bf16 v[116:119], v[168:171], v[190:193], v[116:119]
	v_mfma_f32_16x16x32_bf16 v[112:115], v[176:179], v[190:193], v[112:115]
	v_mfma_f32_16x16x32_bf16 v[100:103], v[168:171], v[198:201], v[100:103]
	v_mfma_f32_16x16x32_bf16 v[96:99], v[176:179], v[198:201], v[96:99]
	v_mfma_f32_16x16x32_bf16 v[84:87], v[168:171], v[206:209], v[84:87]
	v_mfma_f32_16x16x32_bf16 v[80:83], v[176:179], v[206:209], v[80:83]
	v_mfma_f32_16x16x32_bf16 v[68:71], v[168:171], v[214:217], v[68:71]
	v_mfma_f32_16x16x32_bf16 v[64:67], v[176:179], v[214:217], v[64:67]
	v_mfma_f32_16x16x32_bf16 v[116:119], v[172:175], v[194:197], v[116:119]
	v_mfma_f32_16x16x32_bf16 v[112:115], v[180:183], v[194:197], v[112:115]
	v_mfma_f32_16x16x32_bf16 v[100:103], v[172:175], v[202:205], v[100:103]
	v_mfma_f32_16x16x32_bf16 v[96:99], v[180:183], v[202:205], v[96:99]
	v_mfma_f32_16x16x32_bf16 v[84:87], v[172:175], v[210:213], v[84:87]
	v_mfma_f32_16x16x32_bf16 v[80:83], v[180:183], v[210:213], v[80:83]
	v_mfma_f32_16x16x32_bf16 v[68:71], v[172:175], v[218:221], v[68:71]
	v_mfma_f32_16x16x32_bf16 v[64:67], v[180:183], v[218:221], v[64:67]
	s_setprio 0
	s_barrier
	s_add_i32 s38, s55, s8
	v_lshl_add_u64 v[152:153], s[42:43], 0, v[130:131]
	s_mov_b32 m0, s38
	ds_read_b128 v[190:193], v159 offset:16384
	ds_read_b128 v[194:197], v159 offset:17408
	ds_read_b128 v[198:201], v159 offset:18432
	ds_read_b128 v[202:205], v159 offset:19456
	ds_read_b128 v[206:209], v159 offset:20480
	ds_read_b128 v[210:213], v159 offset:21504
	ds_read_b128 v[214:217], v159 offset:22528
	ds_read_b128 v[218:221], v159 offset:23552
	global_load_lds_dwordx4 v[152:153], off
	s_add_i32 m0, s38, 0x2000
	s_add_u32 s38, s42, 0xb0000
	v_lshl_add_u64 v[184:185], s[42:43], 0, v[134:135]
	s_addc_u32 s39, s43, 0
	s_add_i32 s68, s58, s8
	global_load_lds_dwordx4 v[184:185], off
	v_lshl_add_u64 v[222:223], s[38:39], 0, v[130:131]
	s_mov_b32 m0, s68
	v_lshl_add_u64 v[224:225], s[44:45], 0, v[132:133]
	global_load_lds_dwordx4 v[222:223], off
	v_lshl_add_u64 v[222:223], s[38:39], 0, v[134:135]
	s_add_i32 m0, s68, 0x2000
	s_nop 0
	global_load_lds_dwordx4 v[222:223], off
	v_lshl_add_u64 v[222:223], s[44:45], 0, v[128:129]
	s_mov_b32 m0, s9
	s_nop 0
	global_load_lds_dwordx4 v[222:223], off
	s_mov_b32 m0, s18
	s_nop 0
	global_load_lds_dwordx4 v[224:225], off
	s_waitcnt vmcnt(8)
	s_waitcnt lgkmcnt(0)
	s_barrier
; #define PG8_STAGE(bufoff, gbase, voff) do { _Pragma("unroll") for (int _i = 0; _i < 2; ++_i) \
;         __builtin_amdgcn_global_load_lds((const unsigned*)((const char*)(gbase) + (voff)[_i]), (PG8_LAS unsigned*)(lds + (bufoff) + ldsw + _i * 8192), 16, 0, 0); } while (0)
; #define PG8_LDA(dst, b, h) do { _Pragma("unroll") for (int m = 0; m < 4; ++m) _Pragma("unroll") for (int k = 0; k < 2; ++k) dst[m][k] = *(const PG8_LAS bf16x8*)(lds + PG8_SA(b, h) + aoff + m * 2048 + k * 1024); } while (0)
; #define PG8_LDB(dst, b, h) do { _Pragma("unroll") for (int n = 0; n < 2; ++n) _Pragma("unroll") for (int k = 0; k < 2; ++k) dst[n][k] = *(const PG8_LAS bf16x8*)(lds + PG8_SB(b, h) + boff + n * 2048 + k * 1024); } while (0)
; #define PG8_MMA(ai, bj, At, Bt) do { __builtin_amdgcn_s_setprio(1); _Pragma("unroll") for (int m = 0; m < 4; ++m) _Pragma("unroll") for (int n = 0; n < 2; ++n) _Pragma("unroll") for (int k = 0; k < 2; ++k) \
;         acc[ai][bj][m][n] = __builtin_amdgcn_mfma_f32_16x16x32_bf16(Bt[n][k], At[m][k], acc[ai][bj][m][n], 0, 0, 0); __builtin_amdgcn_s_setprio(0); } while (0)
; #define PG8_WAIT_V(n) asm volatile("s_waitcnt vmcnt(" #n ")" ::: "memory")
; #define PG8_WAIT_L(n) asm volatile("s_waitcnt lgkmcnt(" #n ")" ::: "memory")
; #define PG8_BAR __builtin_amdgcn_s_barrier()
; #define PG8_SCHED __builtin_amdgcn_sched_barrier(0)
; template <class Epi, class Sched, bool ALIGN_EPI = false, bool SP2 = false>
; __device__ __forceinline__ void gemm_phase(PG8_LAS unsigned char* lds, const Gemm g, const Sched S, const Epi E) {
;     ...
;             PG8_WAIT_V(8); PG8_WAIT_L(0); PG8_BAR; PG8_MMA(1, 0, At, B0); PG8_MMA(1, 1, At, B1); PG8_BAR; PG8_SCHED;
;             PG8_LDB(B0, 1, 0); PG8_LDB(B1, 1, 1); PG8_SCHED; PG8_LDA(At, 1, 0); PG8_STAGE(PG8_SA(0, 1), a2 + hstep, voffA);
;             PG8_WAIT_V(8); PG8_WAIT_L(0); PG8_BAR; PG8_MMA(0, 0, At, B0); PG8_MMA(0, 1, At, B1); PG8_BAR; PG8_SCHED;
	s_setprio 1
	s_waitcnt lgkmcnt(0)
	v_mfma_f32_16x16x32_bf16 v[60:63], v[144:147], v[190:193], v[60:63]
	v_mfma_f32_16x16x32_bf16 v[56:59], v[160:163], v[190:193], v[56:59]
	v_mfma_f32_16x16x32_bf16 v[44:47], v[144:147], v[198:201], v[44:47]
	v_mfma_f32_16x16x32_bf16 v[40:43], v[160:163], v[198:201], v[40:43]
	v_mfma_f32_16x16x32_bf16 v[28:31], v[144:147], v[206:209], v[28:31]
	v_mfma_f32_16x16x32_bf16 v[24:27], v[160:163], v[206:209], v[24:27]
	v_mfma_f32_16x16x32_bf16 v[12:15], v[144:147], v[214:217], v[12:15]
	v_mfma_f32_16x16x32_bf16 v[8:11], v[160:163], v[214:217], v[8:11]
	v_mfma_f32_16x16x32_bf16 v[60:63], v[148:151], v[194:197], v[60:63]
	v_mfma_f32_16x16x32_bf16 v[56:59], v[164:167], v[194:197], v[56:59]
	v_mfma_f32_16x16x32_bf16 v[44:47], v[148:151], v[202:205], v[44:47]
	v_mfma_f32_16x16x32_bf16 v[40:43], v[164:167], v[202:205], v[40:43]
	v_mfma_f32_16x16x32_bf16 v[28:31], v[148:151], v[210:213], v[28:31]
	v_mfma_f32_16x16x32_bf16 v[24:27], v[164:167], v[210:213], v[24:27]
	v_mfma_f32_16x16x32_bf16 v[12:15], v[148:151], v[218:221], v[12:15]
	v_mfma_f32_16x16x32_bf16 v[8:11], v[164:167], v[218:221], v[8:11]
	s_setprio 0
	s_setprio 1
	v_mfma_f32_16x16x32_bf16 v[52:55], v[168:171], v[190:193], v[52:55]
	v_mfma_f32_16x16x32_bf16 v[48:51], v[176:179], v[190:193], v[48:51]
	v_mfma_f32_16x16x32_bf16 v[36:39], v[168:171], v[198:201], v[36:39]
	v_mfma_f32_16x16x32_bf16 v[32:35], v[176:179], v[198:201], v[32:35]
	v_mfma_f32_16x16x32_bf16 v[20:23], v[168:171], v[206:209], v[20:23]
	v_mfma_f32_16x16x32_bf16 v[16:19], v[176:179], v[206:209], v[16:19]
	v_mfma_f32_16x16x32_bf16 v[4:7], v[168:171], v[214:217], v[4:7]
	v_mfma_f32_16x16x32_bf16 v[0:3], v[176:179], v[214:217], v[0:3]
	v_mfma_f32_16x16x32_bf16 v[52:55], v[172:175], v[194:197], v[52:55]
	v_mfma_f32_16x16x32_bf16 v[48:51], v[180:183], v[194:197], v[48:51]
	v_mfma_f32_16x16x32_bf16 v[36:39], v[172:175], v[202:205], v[36:39]
	v_mfma_f32_16x16x32_bf16 v[32:35], v[180:183], v[202:205], v[32:35]
	v_mfma_f32_16x16x32_bf16 v[20:23], v[172:175], v[210:213], v[20:23]
	v_mfma_f32_16x16x32_bf16 v[16:19], v[180:183], v[210:213], v[16:19]
	v_mfma_f32_16x16x32_bf16 v[4:7], v[172:175], v[218:221], v[4:7]
	v_mfma_f32_16x16x32_bf16 v[0:3], v[180:183], v[218:221], v[0:3]
	s_setprio 0
	s_barrier
	s_add_i32 s68, 0, 0x18000
	s_add_i32 s69, 0, 0x1c000
	v_add_u32_e32 v164, s68, v156
	v_add_u32_e32 v180, s69, v156
	ds_read_b128 v[144:147], v164
	ds_read_b128 v[148:151], v164 offset:1024
	ds_read_b128 v[160:163], v164 offset:2048
	ds_read_b128 v[164:167], v164 offset:3072
	ds_read_b128 v[168:171], v180
	ds_read_b128 v[172:175], v180 offset:1024
	ds_read_b128 v[176:179], v180 offset:2048
	ds_read_b128 v[180:183], v180 offset:3072
	s_add_u32 s38, s44, 0xb0000
	s_addc_u32 s39, s45, 0
	s_mov_b32 m0, s19
	v_lshl_add_u64 v[226:227], s[38:39], 0, v[128:129]
	ds_read_b128 v[190:193], v159 offset:32768
	ds_read_b128 v[194:197], v159 offset:33792
	ds_read_b128 v[198:201], v159 offset:34816
	ds_read_b128 v[202:205], v159 offset:35840
	ds_read_b128 v[206:209], v159 offset:36864
	ds_read_b128 v[210:213], v159 offset:37888
	ds_read_b128 v[214:217], v159 offset:38912
	ds_read_b128 v[218:221], v159 offset:39936
	global_load_lds_dwordx4 v[226:227], off
	v_lshl_add_u64 v[226:227], s[38:39], 0, v[132:133]
	s_mov_b32 m0, s33
	s_nop 0
	global_load_lds_dwordx4 v[226:227], off
	s_waitcnt vmcnt(8)
	s_waitcnt lgkmcnt(0)
	s_barrier
	s_setprio 1
	s_waitcnt lgkmcnt(0)
	v_mfma_f32_16x16x32_bf16 v[124:127], v[144:147], v[190:193], v[124:127]
	v_mfma_f32_16x16x32_bf16 v[120:123], v[160:163], v[190:193], v[120:123]
	v_mfma_f32_16x16x32_bf16 v[108:111], v[144:147], v[198:201], v[108:111]
	v_mfma_f32_16x16x32_bf16 v[104:107], v[160:163], v[198:201], v[104:107]
	v_mfma_f32_16x16x32_bf16 v[92:95], v[144:147], v[206:209], v[92:95]
	v_mfma_f32_16x16x32_bf16 v[88:91], v[160:163], v[206:209], v[88:91]
	v_mfma_f32_16x16x32_bf16 v[76:79], v[144:147], v[214:217], v[76:79]
	v_mfma_f32_16x16x32_bf16 v[72:75], v[160:163], v[214:217], v[72:75]
	v_mfma_f32_16x16x32_bf16 v[124:127], v[148:151], v[194:197], v[124:127]
	v_mfma_f32_16x16x32_bf16 v[120:123], v[164:167], v[194:197], v[120:123]
	v_mfma_f32_16x16x32_bf16 v[108:111], v[148:151], v[202:205], v[108:111]
	v_mfma_f32_16x16x32_bf16 v[104:107], v[164:167], v[202:205], v[104:107]
	v_mfma_f32_16x16x32_bf16 v[92:95], v[148:151], v[210:213], v[92:95]
	v_mfma_f32_16x16x32_bf16 v[88:91], v[164:167], v[210:213], v[88:91]
	v_mfma_f32_16x16x32_bf16 v[76:79], v[148:151], v[218:221], v[76:79]
	v_mfma_f32_16x16x32_bf16 v[72:75], v[164:167], v[218:221], v[72:75]
	s_setprio 0
	s_setprio 1
	v_mfma_f32_16x16x32_bf16 v[116:119], v[168:171], v[190:193], v[116:119]
	v_mfma_f32_16x16x32_bf16 v[112:115], v[176:179], v[190:193], v[112:115]
	v_mfma_f32_16x16x32_bf16 v[100:103], v[168:171], v[198:201], v[100:103]
	v_mfma_f32_16x16x32_bf16 v[96:99], v[176:179], v[198:201], v[96:99]
	v_mfma_f32_16x16x32_bf16 v[84:87], v[168:171], v[206:209], v[84:87]
	v_mfma_f32_16x16x32_bf16 v[80:83], v[176:179], v[206:209], v[80:83]
	v_mfma_f32_16x16x32_bf16 v[68:71], v[168:171], v[214:217], v[68:71]
	v_mfma_f32_16x16x32_bf16 v[64:67], v[176:179], v[214:217], v[64:67]
	v_mfma_f32_16x16x32_bf16 v[116:119], v[172:175], v[194:197], v[116:119]
	v_mfma_f32_16x16x32_bf16 v[112:115], v[180:183], v[194:197], v[112:115]
	v_mfma_f32_16x16x32_bf16 v[100:103], v[172:175], v[202:205], v[100:103]
	v_mfma_f32_16x16x32_bf16 v[96:99], v[180:183], v[202:205], v[96:99]
	v_mfma_f32_16x16x32_bf16 v[84:87], v[172:175], v[210:213], v[84:87]
	v_mfma_f32_16x16x32_bf16 v[80:83], v[180:183], v[210:213], v[80:83]
	v_mfma_f32_16x16x32_bf16 v[68:71], v[172:175], v[218:221], v[68:71]
	v_mfma_f32_16x16x32_bf16 v[64:67], v[180:183], v[218:221], v[64:67]
	s_setprio 0
	s_barrier
; #define PG8_STAGE(bufoff, gbase, voff) do { _Pragma("unroll") for (int _i = 0; _i < 2; ++_i) \
;         __builtin_amdgcn_global_load_lds((const unsigned*)((const char*)(gbase) + (voff)[_i]), (PG8_LAS unsigned*)(lds + (bufoff) + ldsw + _i * 8192), 16, 0, 0); } while (0)
; #define PG8_LDA(dst, b, h) do { _Pragma("unroll") for (int m = 0; m < 4; ++m) _Pragma("unroll") for (int k = 0; k < 2; ++k) dst[m][k] = *(const PG8_LAS bf16x8*)(lds + PG8_SA(b, h) + aoff + m * 2048 + k * 1024); } while (0)
; #define PG8_MMA(ai, bj, At, Bt) do { __builtin_amdgcn_s_setprio(1); _Pragma("unroll") for (int m = 0; m < 4; ++m) _Pragma("unroll") for (int n = 0; n < 2; ++n) _Pragma("unroll") for (int k = 0; k < 2; ++k) \
;         acc[ai][bj][m][n] = __builtin_amdgcn_mfma_f32_16x16x32_bf16(Bt[n][k], At[m][k], acc[ai][bj][m][n], 0, 0, 0); __builtin_amdgcn_s_setprio(0); } while (0)
; #define PG8_WAIT_V(n) asm volatile("s_waitcnt vmcnt(" #n ")" ::: "memory")
; #define PG8_WAIT_L(n) asm volatile("s_waitcnt lgkmcnt(" #n ")" ::: "memory")
; #define PG8_BAR __builtin_amdgcn_s_barrier()
; #define PG8_SCHED __builtin_amdgcn_sched_barrier(0)
; template <class Epi, class Sched, bool ALIGN_EPI = false, bool SP2 = false>
; __device__ __forceinline__ void gemm_phase(PG8_LAS unsigned char* lds, const Gemm g, const Sched S, const Epi E) {
;     ...
;         for (int t = 0; t < nt; t += 2) {
;             if constexpr (Epi::MIDT >= 0) { if (t == Epi::MIDT) E.mid(acc, cur, wr, fr); }
;             const bool last = (t == nt - 2);
;             const char* a1 = cA + (size_t)(t + 1) * kstep;
;             const char* a2 = last ? nA : cA + (size_t)(t + 2) * kstep; const char* b2 = last ? nB : cB + (size_t)(t + 2) * kstep;
;             const char* a3 = a2 + kstep; const char* b3 = b2 + kstep;
;     ...
;             PG8_LDA(At, 1, 1); PG8_STAGE(PG8_SB(1, 0), b3, voffB); PG8_STAGE(PG8_SB(1, 1), b3 + hstep, voffB); PG8_STAGE(PG8_SA(1, 0), a3, voffA);
;             PG8_WAIT_V(8); PG8_WAIT_L(0); PG8_BAR; PG8_MMA(1, 0, At, B0); PG8_MMA(1, 1, At, B1); PG8_BAR; PG8_SCHED;
	s_add_i32 s38, s68, s8
	v_lshl_add_u64 v[152:153], v[152:153], 0, s[12:13]
	s_mov_b32 m0, s38
	ds_read_b128 v[190:193], v159 offset:49152
	ds_read_b128 v[194:197], v159 offset:50176
	ds_read_b128 v[198:201], v159 offset:51200
	ds_read_b128 v[202:205], v159 offset:52224
	ds_read_b128 v[206:209], v159 offset:53248
	ds_read_b128 v[210:213], v159 offset:54272
	ds_read_b128 v[214:217], v159 offset:55296
	ds_read_b128 v[218:221], v159 offset:56320
	global_load_lds_dwordx4 v[152:153], off
	s_add_i32 m0, s38, 0x2000
	s_add_u32 s38, s42, 0xb0080
	v_lshl_add_u64 v[152:153], v[184:185], 0, s[12:13]
	s_addc_u32 s39, s43, 0
	s_add_i32 s42, s69, s8
	global_load_lds_dwordx4 v[152:153], off
	v_lshl_add_u64 v[152:153], s[38:39], 0, v[130:131]
	s_mov_b32 m0, s42
	s_nop 0
	global_load_lds_dwordx4 v[152:153], off
	v_lshl_add_u64 v[152:153], s[38:39], 0, v[134:135]
	s_add_i32 m0, s42, 0x2000
	s_nop 0
	global_load_lds_dwordx4 v[152:153], off
	v_lshl_add_u64 v[152:153], v[222:223], 0, s[12:13]
	s_mov_b32 m0, s49
	s_nop 0
	global_load_lds_dwordx4 v[152:153], off
	v_lshl_add_u64 v[152:153], v[224:225], 0, s[12:13]
	s_mov_b32 m0, s50
	s_nop 0
	global_load_lds_dwordx4 v[152:153], off
	s_waitcnt vmcnt(8)
	s_waitcnt lgkmcnt(0)
	s_barrier
	s_setprio 1
	s_waitcnt lgkmcnt(0)
	v_mfma_f32_16x16x32_bf16 v[60:63], v[144:147], v[190:193], v[60:63]
	v_mfma_f32_16x16x32_bf16 v[56:59], v[160:163], v[190:193], v[56:59]
	v_mfma_f32_16x16x32_bf16 v[44:47], v[144:147], v[198:201], v[44:47]
	v_mfma_f32_16x16x32_bf16 v[40:43], v[160:163], v[198:201], v[40:43]
	v_mfma_f32_16x16x32_bf16 v[28:31], v[144:147], v[206:209], v[28:31]
	v_mfma_f32_16x16x32_bf16 v[24:27], v[160:163], v[206:209], v[24:27]
	v_mfma_f32_16x16x32_bf16 v[12:15], v[144:147], v[214:217], v[12:15]
	v_mfma_f32_16x16x32_bf16 v[8:11], v[160:163], v[214:217], v[8:11]
	v_mfma_f32_16x16x32_bf16 v[60:63], v[148:151], v[194:197], v[60:63]
	v_mfma_f32_16x16x32_bf16 v[56:59], v[164:167], v[194:197], v[56:59]
	v_mfma_f32_16x16x32_bf16 v[44:47], v[148:151], v[202:205], v[44:47]
	v_mfma_f32_16x16x32_bf16 v[40:43], v[164:167], v[202:205], v[40:43]
	v_mfma_f32_16x16x32_bf16 v[28:31], v[148:151], v[210:213], v[28:31]
	v_mfma_f32_16x16x32_bf16 v[24:27], v[164:167], v[210:213], v[24:27]
	v_mfma_f32_16x16x32_bf16 v[12:15], v[148:151], v[218:221], v[12:15]
	v_mfma_f32_16x16x32_bf16 v[8:11], v[164:167], v[218:221], v[8:11]
	s_setprio 0
	s_setprio 1
	v_mfma_f32_16x16x32_bf16 v[52:55], v[168:171], v[190:193], v[52:55]
	v_mfma_f32_16x16x32_bf16 v[48:51], v[176:179], v[190:193], v[48:51]
	v_mfma_f32_16x16x32_bf16 v[36:39], v[168:171], v[198:201], v[36:39]
	v_mfma_f32_16x16x32_bf16 v[32:35], v[176:179], v[198:201], v[32:35]
	v_mfma_f32_16x16x32_bf16 v[20:23], v[168:171], v[206:209], v[20:23]
	v_mfma_f32_16x16x32_bf16 v[16:19], v[176:179], v[206:209], v[16:19]
	v_mfma_f32_16x16x32_bf16 v[4:7], v[168:171], v[214:217], v[4:7]
	v_mfma_f32_16x16x32_bf16 v[0:3], v[176:179], v[214:217], v[0:3]
	v_mfma_f32_16x16x32_bf16 v[52:55], v[172:175], v[194:197], v[52:55]
	v_mfma_f32_16x16x32_bf16 v[48:51], v[180:183], v[194:197], v[48:51]
	v_mfma_f32_16x16x32_bf16 v[36:39], v[172:175], v[202:205], v[36:39]
	v_mfma_f32_16x16x32_bf16 v[32:35], v[180:183], v[202:205], v[32:35]
	s_add_i32 s65, s65, 2
	s_add_u32 s63, s63, 0x100
	s_addc_u32 s64, s64, 0
	s_cmp_gt_u32 s65, 41
	s_mov_b64 s[38:39], s[40:41]
	v_mfma_f32_16x16x32_bf16 v[20:23], v[172:175], v[210:213], v[20:23]
	v_mfma_f32_16x16x32_bf16 v[16:19], v[180:183], v[210:213], v[16:19]
	v_mfma_f32_16x16x32_bf16 v[4:7], v[172:175], v[218:221], v[4:7]
	v_mfma_f32_16x16x32_bf16 v[0:3], v[180:183], v[218:221], v[0:3]
	s_setprio 0
	s_barrier
	s_cbranch_scc0 .LBB0_356
	s_and_b64 vcc, exec, s[14:15]
	s_cbranch_vccz .LBB0_359
	s_barrier

; #define PG8_STAGE(bufoff, gbase, voff) do { _Pragma("unroll") for (int _i = 0; _i < 2; ++_i) \
;         __builtin_amdgcn_global_load_lds((const unsigned*)((const char*)(gbase) + (voff)[_i]), (PG8_LAS unsigned*)(lds + (bufoff) + ldsw + _i * 8192), 16, 0, 0); } while (0)
; #define PG8_LDA(dst, b, h) do { _Pragma("unroll") for (int m = 0; m < 4; ++m) _Pragma("unroll") for (int k = 0; k < 2; ++k) dst[m][k] = *(const PG8_LAS bf16x8*)(lds + PG8_SA(b, h) + aoff + m * 2048 + k * 1024); } while (0)
; #define PG8_LDB(dst, b, h) do { _Pragma("unroll") for (int n = 0; n < 2; ++n) _Pragma("unroll") for (int k = 0; k < 2; ++k) dst[n][k] = *(const PG8_LAS bf16x8*)(lds + PG8_SB(b, h) + boff + n * 2048 + k * 1024); } while (0)
; #define PG8_MMA(ai, bj, At, Bt) do { __builtin_amdgcn_s_setprio(1); _Pragma("unroll") for (int m = 0; m < 4; ++m) _Pragma("unroll") for (int n = 0; n < 2; ++n) _Pragma("unroll") for (int k = 0; k < 2; ++k) \
;         acc[ai][bj][m][n] = __builtin_amdgcn_mfma_f32_16x16x32_bf16(Bt[n][k], At[m][k], acc[ai][bj][m][n], 0, 0, 0); __builtin_amdgcn_s_setprio(0); } while (0)
; #define PG8_WAIT_V(n) asm volatile("s_waitcnt vmcnt(" #n ")" ::: "memory")
; #define PG8_WAIT_L(n) asm volatile("s_waitcnt lgkmcnt(" #n ")" ::: "memory")
; #define PG8_BAR __builtin_amdgcn_s_barrier()
; #define PG8_SCHED __builtin_amdgcn_sched_barrier(0)
; template <class Epi, class Sched, bool ALIGN_EPI = false, bool SP2 = false>
; __device__ __forceinline__ void gemm_phase(PG8_LAS unsigned char* lds, const Gemm g, const Sched S, const Epi E) {
;     ...
;             PG8_LDB(B0, 0, 0); PG8_LDB(B1, 0, 1); PG8_SCHED; PG8_LDA(At, 0, 0); PG8_STAGE(PG8_SA(1, 1), a1 + hstep, voffA);
;             PG8_WAIT_V(8); PG8_WAIT_L(0); PG8_BAR; PG8_MMA(0, 0, At, B0); PG8_MMA(0, 1, At, B1); PG8_BAR; PG8_SCHED;
;             PG8_LDA(At, 0, 1); PG8_STAGE(PG8_SB(0, 0), b2, voffB); PG8_STAGE(PG8_SB(0, 1), b2 + hstep, voffB); PG8_STAGE(PG8_SA(0, 0), a2, voffA);
;             PG8_WAIT_V(8); PG8_WAIT_L(0); PG8_BAR; PG8_MMA(1, 0, At, B0); PG8_MMA(1, 1, At, B1); PG8_BAR; PG8_SCHED;
.LBB0_484:
	ds_read_b128 v[128:131], v193
	ds_read_b128 v[132:135], v193 offset:1024
	ds_read_b128 v[150:153], v193 offset:2048
	ds_read_b128 v[154:157], v193 offset:3072
	ds_read_b128 v[158:161], v194
	ds_read_b128 v[162:165], v194 offset:1024
	ds_read_b128 v[166:169], v194 offset:2048
	ds_read_b128 v[170:173], v194 offset:3072
	s_add_u32 s10, s6, 0xfffc0080
	s_addc_u32 s11, s7, -1
	s_cmp_eq_u32 s61, 12
	s_cselect_b32 s93, s1, s11
	s_cselect_b32 s92, s33, s10
	s_cselect_b32 s11, s36, s60
	s_cselect_b32 s10, s58, s59
	v_lshl_add_u64 v[220:221], s[6:7], 0, v[142:143]
	s_add_i32 m0, s19, 0xc000
	ds_read_b128 v[174:177], v195
	ds_read_b128 v[178:181], v195 offset:1024
	ds_read_b128 v[182:185], v195 offset:2048
	ds_read_b128 v[200:203], v195 offset:3072
	ds_read_b128 v[204:207], v195 offset:4096
	ds_read_b128 v[208:211], v195 offset:5120
	ds_read_b128 v[212:215], v195 offset:6144
	ds_read_b128 v[216:219], v195 offset:7168
	global_load_lds_dwordx4 v[220:221], off
	v_lshl_add_u64 v[220:221], s[6:7], 0, v[144:145]
	s_add_i32 m0, s19, 0xe000
	s_nop 0
	global_load_lds_dwordx4 v[220:221], off
	s_waitcnt vmcnt(8)
	s_waitcnt lgkmcnt(0)
	s_barrier
	s_setprio 1
	s_waitcnt lgkmcnt(0)
	v_mfma_f32_16x16x32_bf16 v[124:127], v[128:131], v[174:177], v[124:127]
	v_mfma_f32_16x16x32_bf16 v[120:123], v[150:153], v[174:177], v[120:123]
	v_mfma_f32_16x16x32_bf16 v[108:111], v[128:131], v[182:185], v[108:111]
	v_mfma_f32_16x16x32_bf16 v[104:107], v[150:153], v[182:185], v[104:107]
	v_mfma_f32_16x16x32_bf16 v[92:95], v[128:131], v[204:207], v[92:95]
	v_mfma_f32_16x16x32_bf16 v[88:91], v[150:153], v[204:207], v[88:91]
	v_mfma_f32_16x16x32_bf16 v[76:79], v[128:131], v[212:215], v[76:79]
	v_mfma_f32_16x16x32_bf16 v[72:75], v[150:153], v[212:215], v[72:75]
	v_mfma_f32_16x16x32_bf16 v[124:127], v[132:135], v[178:181], v[124:127]
	v_mfma_f32_16x16x32_bf16 v[120:123], v[154:157], v[178:181], v[120:123]
	v_mfma_f32_16x16x32_bf16 v[108:111], v[132:135], v[200:203], v[108:111]
	v_mfma_f32_16x16x32_bf16 v[104:107], v[154:157], v[200:203], v[104:107]
	v_mfma_f32_16x16x32_bf16 v[92:95], v[132:135], v[208:211], v[92:95]
	v_mfma_f32_16x16x32_bf16 v[88:91], v[154:157], v[208:211], v[88:91]
	v_mfma_f32_16x16x32_bf16 v[76:79], v[132:135], v[216:219], v[76:79]
	v_mfma_f32_16x16x32_bf16 v[72:75], v[154:157], v[216:219], v[72:75]
	s_setprio 0
	s_setprio 1
	v_mfma_f32_16x16x32_bf16 v[116:119], v[158:161], v[174:177], v[116:119]
	v_mfma_f32_16x16x32_bf16 v[112:115], v[166:169], v[174:177], v[112:115]
	v_mfma_f32_16x16x32_bf16 v[100:103], v[158:161], v[182:185], v[100:103]
	v_mfma_f32_16x16x32_bf16 v[96:99], v[166:169], v[182:185], v[96:99]
	v_mfma_f32_16x16x32_bf16 v[84:87], v[158:161], v[204:207], v[84:87]
	v_mfma_f32_16x16x32_bf16 v[80:83], v[166:169], v[204:207], v[80:83]
	v_mfma_f32_16x16x32_bf16 v[68:71], v[158:161], v[212:215], v[68:71]
	v_mfma_f32_16x16x32_bf16 v[64:67], v[166:169], v[212:215], v[64:67]
	v_mfma_f32_16x16x32_bf16 v[116:119], v[162:165], v[178:181], v[116:119]
	v_mfma_f32_16x16x32_bf16 v[112:115], v[170:173], v[178:181], v[112:115]
	v_mfma_f32_16x16x32_bf16 v[100:103], v[162:165], v[200:203], v[100:103]
	v_mfma_f32_16x16x32_bf16 v[96:99], v[170:173], v[200:203], v[96:99]
	v_mfma_f32_16x16x32_bf16 v[84:87], v[162:165], v[208:211], v[84:87]
	v_mfma_f32_16x16x32_bf16 v[80:83], v[170:173], v[208:211], v[80:83]
	v_mfma_f32_16x16x32_bf16 v[68:71], v[162:165], v[216:219], v[68:71]
	v_mfma_f32_16x16x32_bf16 v[64:67], v[170:173], v[216:219], v[64:67]
	s_setprio 0
	s_barrier
	s_add_i32 s85, s65, s18
	v_lshl_add_u64 v[220:221], s[10:11], 0, v[136:137]
	s_mov_b32 m0, s85
	ds_read_b128 v[174:177], v195 offset:16384
	ds_read_b128 v[178:181], v195 offset:17408
	ds_read_b128 v[182:185], v195 offset:18432
	ds_read_b128 v[200:203], v195 offset:19456
	ds_read_b128 v[204:207], v195 offset:20480
	ds_read_b128 v[208:211], v195 offset:21504
	ds_read_b128 v[212:215], v195 offset:22528
	ds_read_b128 v[216:219], v195 offset:23552
	global_load_lds_dwordx4 v[220:221], off
	s_add_i32 m0, s85, 0x2000
	s_add_u32 s96, s10, 0x40000
	v_lshl_add_u64 v[222:223], s[10:11], 0, v[138:139]
	s_addc_u32 s97, s11, 0
	s_add_i32 s85, s46, s18
	global_load_lds_dwordx4 v[222:223], off
	v_lshl_add_u64 v[224:225], s[96:97], 0, v[136:137]
	s_mov_b32 m0, s85
	v_lshl_add_u64 v[226:227], s[92:93], 0, v[138:139]
	global_load_lds_dwordx4 v[224:225], off
	v_lshl_add_u64 v[224:225], s[96:97], 0, v[138:139]
	s_add_i32 m0, s85, 0x2000
	s_nop 0
	global_load_lds_dwordx4 v[224:225], off
	v_lshl_add_u64 v[224:225], s[92:93], 0, v[136:137]
	s_mov_b32 m0, s19
	s_nop 0
	global_load_lds_dwordx4 v[224:225], off
	s_mov_b32 m0, s95
	s_nop 0
	global_load_lds_dwordx4 v[226:227], off
	s_waitcnt vmcnt(8)
	s_waitcnt lgkmcnt(0)
	s_barrier
; #define PG8_STAGE(bufoff, gbase, voff) do { _Pragma("unroll") for (int _i = 0; _i < 2; ++_i) \
;         __builtin_amdgcn_global_load_lds((const unsigned*)((const char*)(gbase) + (voff)[_i]), (PG8_LAS unsigned*)(lds + (bufoff) + ldsw + _i * 8192), 16, 0, 0); } while (0)
; #define PG8_LDA(dst, b, h) do { _Pragma("unroll") for (int m = 0; m < 4; ++m) _Pragma("unroll") for (int k = 0; k < 2; ++k) dst[m][k] = *(const PG8_LAS bf16x8*)(lds + PG8_SA(b, h) + aoff + m * 2048 + k * 1024); } while (0)
; #define PG8_LDB(dst, b, h) do { _Pragma("unroll") for (int n = 0; n < 2; ++n) _Pragma("unroll") for (int k = 0; k < 2; ++k) dst[n][k] = *(const PG8_LAS bf16x8*)(lds + PG8_SB(b, h) + boff + n * 2048 + k * 1024); } while (0)
; #define PG8_MMA(ai, bj, At, Bt) do { __builtin_amdgcn_s_setprio(1); _Pragma("unroll") for (int m = 0; m < 4; ++m) _Pragma("unroll") for (int n = 0; n < 2; ++n) _Pragma("unroll") for (int k = 0; k < 2; ++k) \
;         acc[ai][bj][m][n] = __builtin_amdgcn_mfma_f32_16x16x32_bf16(Bt[n][k], At[m][k], acc[ai][bj][m][n], 0, 0, 0); __builtin_amdgcn_s_setprio(0); } while (0)
; #define PG8_WAIT_V(n) asm volatile("s_waitcnt vmcnt(" #n ")" ::: "memory")
; #define PG8_WAIT_L(n) asm volatile("s_waitcnt lgkmcnt(" #n ")" ::: "memory")
; #define PG8_BAR __builtin_amdgcn_s_barrier()
; #define PG8_SCHED __builtin_amdgcn_sched_barrier(0)
; template <class Epi, class Sched, bool ALIGN_EPI = false, bool SP2 = false>
; __device__ __forceinline__ void gemm_phase(PG8_LAS unsigned char* lds, const Gemm g, const Sched S, const Epi E) {
;     ...
;             PG8_WAIT_V(8); PG8_WAIT_L(0); PG8_BAR; PG8_MMA(1, 0, At, B0); PG8_MMA(1, 1, At, B1); PG8_BAR; PG8_SCHED;
;             PG8_LDB(B0, 1, 0); PG8_LDB(B1, 1, 1); PG8_SCHED; PG8_LDA(At, 1, 0); PG8_STAGE(PG8_SA(0, 1), a2 + hstep, voffA);
;             PG8_WAIT_V(8); PG8_WAIT_L(0); PG8_BAR; PG8_MMA(0, 0, At, B0); PG8_MMA(0, 1, At, B1); PG8_BAR; PG8_SCHED;
	s_setprio 1
	s_waitcnt lgkmcnt(0)
	v_mfma_f32_16x16x32_bf16 v[60:63], v[128:131], v[174:177], v[60:63]
	v_mfma_f32_16x16x32_bf16 v[56:59], v[150:153], v[174:177], v[56:59]
	v_mfma_f32_16x16x32_bf16 v[44:47], v[128:131], v[182:185], v[44:47]
	v_mfma_f32_16x16x32_bf16 v[40:43], v[150:153], v[182:185], v[40:43]
	v_mfma_f32_16x16x32_bf16 v[28:31], v[128:131], v[204:207], v[28:31]
	v_mfma_f32_16x16x32_bf16 v[24:27], v[150:153], v[204:207], v[24:27]
	v_mfma_f32_16x16x32_bf16 v[12:15], v[128:131], v[212:215], v[12:15]
	v_mfma_f32_16x16x32_bf16 v[8:11], v[150:153], v[212:215], v[8:11]
	v_mfma_f32_16x16x32_bf16 v[60:63], v[132:135], v[178:181], v[60:63]
	v_mfma_f32_16x16x32_bf16 v[56:59], v[154:157], v[178:181], v[56:59]
	v_mfma_f32_16x16x32_bf16 v[44:47], v[132:135], v[200:203], v[44:47]
	v_mfma_f32_16x16x32_bf16 v[40:43], v[154:157], v[200:203], v[40:43]
	v_mfma_f32_16x16x32_bf16 v[28:31], v[132:135], v[208:211], v[28:31]
	v_mfma_f32_16x16x32_bf16 v[24:27], v[154:157], v[208:211], v[24:27]
	v_mfma_f32_16x16x32_bf16 v[12:15], v[132:135], v[216:219], v[12:15]
	v_mfma_f32_16x16x32_bf16 v[8:11], v[154:157], v[216:219], v[8:11]
	s_setprio 0
	s_setprio 1
	v_mfma_f32_16x16x32_bf16 v[52:55], v[158:161], v[174:177], v[52:55]
	v_mfma_f32_16x16x32_bf16 v[48:51], v[166:169], v[174:177], v[48:51]
	v_mfma_f32_16x16x32_bf16 v[36:39], v[158:161], v[182:185], v[36:39]
	v_mfma_f32_16x16x32_bf16 v[32:35], v[166:169], v[182:185], v[32:35]
	v_mfma_f32_16x16x32_bf16 v[20:23], v[158:161], v[204:207], v[20:23]
	v_mfma_f32_16x16x32_bf16 v[16:19], v[166:169], v[204:207], v[16:19]
	v_mfma_f32_16x16x32_bf16 v[4:7], v[158:161], v[212:215], v[4:7]
	v_mfma_f32_16x16x32_bf16 v[0:3], v[166:169], v[212:215], v[0:3]
	v_mfma_f32_16x16x32_bf16 v[52:55], v[162:165], v[178:181], v[52:55]
	v_mfma_f32_16x16x32_bf16 v[48:51], v[170:173], v[178:181], v[48:51]
	v_mfma_f32_16x16x32_bf16 v[36:39], v[162:165], v[200:203], v[36:39]
	v_mfma_f32_16x16x32_bf16 v[32:35], v[170:173], v[200:203], v[32:35]
	v_mfma_f32_16x16x32_bf16 v[20:23], v[162:165], v[208:211], v[20:23]
	v_mfma_f32_16x16x32_bf16 v[16:19], v[170:173], v[208:211], v[16:19]
	v_mfma_f32_16x16x32_bf16 v[4:7], v[162:165], v[216:219], v[4:7]
	v_mfma_f32_16x16x32_bf16 v[0:3], v[170:173], v[216:219], v[0:3]
	s_setprio 0
	s_barrier
	s_add_i32 s85, 0, 0x18000
	v_add_u32_e32 v140, s85, v191
	s_add_i32 s87, 0, 0x1c000
	ds_read_b128 v[128:131], v140
	ds_read_b128 v[132:135], v140 offset:1024
	ds_read_b128 v[150:153], v140 offset:2048
	ds_read_b128 v[154:157], v140 offset:3072
	v_add_u32_e32 v140, s87, v191
	ds_read_b128 v[158:161], v140
	ds_read_b128 v[162:165], v140 offset:1024
	ds_read_b128 v[166:169], v140 offset:2048
	ds_read_b128 v[170:173], v140 offset:3072
	s_add_u32 s92, s92, 0x40000
	s_addc_u32 s93, s93, 0
	s_mov_b32 m0, s8
	v_lshl_add_u64 v[228:229], s[92:93], 0, v[136:137]
	ds_read_b128 v[174:177], v195 offset:32768
	ds_read_b128 v[178:181], v195 offset:33792
	ds_read_b128 v[182:185], v195 offset:34816
	ds_read_b128 v[200:203], v195 offset:35840
	ds_read_b128 v[204:207], v195 offset:36864
	ds_read_b128 v[208:211], v195 offset:37888
	ds_read_b128 v[212:215], v195 offset:38912
	ds_read_b128 v[216:219], v195 offset:39936
	global_load_lds_dwordx4 v[228:229], off
	v_lshl_add_u64 v[228:229], s[92:93], 0, v[138:139]
	s_mov_b32 m0, s9
	s_nop 0
	global_load_lds_dwordx4 v[228:229], off
	s_waitcnt vmcnt(8)
	s_waitcnt lgkmcnt(0)
	s_barrier
	s_setprio 1
	s_waitcnt lgkmcnt(0)
	v_mfma_f32_16x16x32_bf16 v[124:127], v[128:131], v[174:177], v[124:127]
	v_mfma_f32_16x16x32_bf16 v[120:123], v[150:153], v[174:177], v[120:123]
	v_mfma_f32_16x16x32_bf16 v[108:111], v[128:131], v[182:185], v[108:111]
	v_mfma_f32_16x16x32_bf16 v[104:107], v[150:153], v[182:185], v[104:107]
	v_mfma_f32_16x16x32_bf16 v[92:95], v[128:131], v[204:207], v[92:95]
	v_mfma_f32_16x16x32_bf16 v[88:91], v[150:153], v[204:207], v[88:91]
	v_mfma_f32_16x16x32_bf16 v[76:79], v[128:131], v[212:215], v[76:79]
	v_mfma_f32_16x16x32_bf16 v[72:75], v[150:153], v[212:215], v[72:75]
	v_mfma_f32_16x16x32_bf16 v[124:127], v[132:135], v[178:181], v[124:127]
	v_mfma_f32_16x16x32_bf16 v[120:123], v[154:157], v[178:181], v[120:123]
	v_mfma_f32_16x16x32_bf16 v[108:111], v[132:135], v[200:203], v[108:111]
	v_mfma_f32_16x16x32_bf16 v[104:107], v[154:157], v[200:203], v[104:107]
	v_mfma_f32_16x16x32_bf16 v[92:95], v[132:135], v[208:211], v[92:95]
	v_mfma_f32_16x16x32_bf16 v[88:91], v[154:157], v[208:211], v[88:91]
	v_mfma_f32_16x16x32_bf16 v[76:79], v[132:135], v[216:219], v[76:79]
	v_mfma_f32_16x16x32_bf16 v[72:75], v[154:157], v[216:219], v[72:75]
	s_setprio 0
	s_setprio 1
	v_mfma_f32_16x16x32_bf16 v[116:119], v[158:161], v[174:177], v[116:119]
	v_mfma_f32_16x16x32_bf16 v[112:115], v[166:169], v[174:177], v[112:115]
	v_mfma_f32_16x16x32_bf16 v[100:103], v[158:161], v[182:185], v[100:103]
	v_mfma_f32_16x16x32_bf16 v[96:99], v[166:169], v[182:185], v[96:99]
	v_mfma_f32_16x16x32_bf16 v[84:87], v[158:161], v[204:207], v[84:87]
	v_mfma_f32_16x16x32_bf16 v[80:83], v[166:169], v[204:207], v[80:83]
	v_mfma_f32_16x16x32_bf16 v[68:71], v[158:161], v[212:215], v[68:71]
	v_mfma_f32_16x16x32_bf16 v[64:67], v[166:169], v[212:215], v[64:67]
	v_mfma_f32_16x16x32_bf16 v[116:119], v[162:165], v[178:181], v[116:119]
	v_mfma_f32_16x16x32_bf16 v[112:115], v[170:173], v[178:181], v[112:115]
	v_mfma_f32_16x16x32_bf16 v[100:103], v[162:165], v[200:203], v[100:103]
	v_mfma_f32_16x16x32_bf16 v[96:99], v[170:173], v[200:203], v[96:99]
	v_mfma_f32_16x16x32_bf16 v[84:87], v[162:165], v[208:211], v[84:87]
	v_mfma_f32_16x16x32_bf16 v[80:83], v[170:173], v[208:211], v[80:83]
	v_mfma_f32_16x16x32_bf16 v[68:71], v[162:165], v[216:219], v[68:71]
	v_mfma_f32_16x16x32_bf16 v[64:67], v[170:173], v[216:219], v[64:67]
	s_setprio 0
	s_barrier
; #define PG8_STAGE(bufoff, gbase, voff) do { _Pragma("unroll") for (int _i = 0; _i < 2; ++_i) \
;         __builtin_amdgcn_global_load_lds((const unsigned*)((const char*)(gbase) + (voff)[_i]), (PG8_LAS unsigned*)(lds + (bufoff) + ldsw + _i * 8192), 16, 0, 0); } while (0)
; #define PG8_LDA(dst, b, h) do { _Pragma("unroll") for (int m = 0; m < 4; ++m) _Pragma("unroll") for (int k = 0; k < 2; ++k) dst[m][k] = *(const PG8_LAS bf16x8*)(lds + PG8_SA(b, h) + aoff + m * 2048 + k * 1024); } while (0)
; #define PG8_MMA(ai, bj, At, Bt) do { __builtin_amdgcn_s_setprio(1); _Pragma("unroll") for (int m = 0; m < 4; ++m) _Pragma("unroll") for (int n = 0; n < 2; ++n) _Pragma("unroll") for (int k = 0; k < 2; ++k) \
;         acc[ai][bj][m][n] = __builtin_amdgcn_mfma_f32_16x16x32_bf16(Bt[n][k], At[m][k], acc[ai][bj][m][n], 0, 0, 0); __builtin_amdgcn_s_setprio(0); } while (0)
; #define PG8_WAIT_V(n) asm volatile("s_waitcnt vmcnt(" #n ")" ::: "memory")
; #define PG8_WAIT_L(n) asm volatile("s_waitcnt lgkmcnt(" #n ")" ::: "memory")
; #define PG8_BAR __builtin_amdgcn_s_barrier()
; #define PG8_SCHED __builtin_amdgcn_sched_barrier(0)
; template <class Epi, class Sched, bool ALIGN_EPI = false, bool SP2 = false>
; __device__ __forceinline__ void gemm_phase(PG8_LAS unsigned char* lds, const Gemm g, const Sched S, const Epi E) {
;     ...
;         for (int t = 0; t < nt; t += 2) {
;             if constexpr (Epi::MIDT >= 0) { if (t == Epi::MIDT) E.mid(acc, cur, wr, fr); }
;             const bool last = (t == nt - 2);
;             const char* a1 = cA + (size_t)(t + 1) * kstep;
;             const char* a2 = last ? nA : cA + (size_t)(t + 2) * kstep; const char* b2 = last ? nB : cB + (size_t)(t + 2) * kstep;
;     ...
;             PG8_LDA(At, 1, 1); PG8_STAGE(PG8_SB(1, 0), b3, voffB); PG8_STAGE(PG8_SB(1, 1), b3 + hstep, voffB); PG8_STAGE(PG8_SA(1, 0), a3, voffA);
;             PG8_WAIT_V(8); PG8_WAIT_L(0); PG8_BAR; PG8_MMA(1, 0, At, B0); PG8_MMA(1, 1, At, B1); PG8_BAR; PG8_SCHED;
	s_add_i32 s85, s85, s18
	v_lshl_add_u64 v[220:221], v[220:221], 0, s[52:53]
	s_mov_b32 m0, s85
	ds_read_b128 v[174:177], v195 offset:49152
	ds_read_b128 v[178:181], v195 offset:50176
	ds_read_b128 v[182:185], v195 offset:51200
	ds_read_b128 v[200:203], v195 offset:52224
	ds_read_b128 v[204:207], v195 offset:53248
	ds_read_b128 v[208:211], v195 offset:54272
	ds_read_b128 v[212:215], v195 offset:55296
	ds_read_b128 v[216:219], v195 offset:56320
	global_load_lds_dwordx4 v[220:221], off
	s_add_i32 m0, s85, 0x2000
	s_add_u32 s10, s10, 0x40080
	v_lshl_add_u64 v[220:221], v[222:223], 0, s[52:53]
	s_addc_u32 s11, s11, 0
	s_add_i32 s85, s87, s18
	global_load_lds_dwordx4 v[220:221], off
	v_lshl_add_u64 v[220:221], s[10:11], 0, v[136:137]
	s_mov_b32 m0, s85
	s_nop 0
	global_load_lds_dwordx4 v[220:221], off
	v_lshl_add_u64 v[220:221], s[10:11], 0, v[138:139]
	s_add_i32 m0, s85, 0x2000
	s_nop 0
	global_load_lds_dwordx4 v[220:221], off
	v_lshl_add_u64 v[220:221], v[224:225], 0, s[52:53]
	s_mov_b32 m0, s67
	s_nop 0
	global_load_lds_dwordx4 v[220:221], off
	v_lshl_add_u64 v[220:221], v[226:227], 0, s[52:53]
	s_mov_b32 m0, s54
	s_nop 0
	global_load_lds_dwordx4 v[220:221], off
	s_waitcnt vmcnt(8)
	s_waitcnt lgkmcnt(0)
	s_barrier
	s_setprio 1
	s_waitcnt lgkmcnt(0)
	v_mfma_f32_16x16x32_bf16 v[60:63], v[128:131], v[174:177], v[60:63]
	v_mfma_f32_16x16x32_bf16 v[56:59], v[150:153], v[174:177], v[56:59]
	v_mfma_f32_16x16x32_bf16 v[44:47], v[128:131], v[182:185], v[44:47]
	v_mfma_f32_16x16x32_bf16 v[40:43], v[150:153], v[182:185], v[40:43]
	v_mfma_f32_16x16x32_bf16 v[28:31], v[128:131], v[204:207], v[28:31]
	v_mfma_f32_16x16x32_bf16 v[24:27], v[150:153], v[204:207], v[24:27]
	v_mfma_f32_16x16x32_bf16 v[12:15], v[128:131], v[212:215], v[12:15]
	v_mfma_f32_16x16x32_bf16 v[8:11], v[150:153], v[212:215], v[8:11]
	v_mfma_f32_16x16x32_bf16 v[60:63], v[132:135], v[178:181], v[60:63]
	v_mfma_f32_16x16x32_bf16 v[56:59], v[154:157], v[178:181], v[56:59]
	v_mfma_f32_16x16x32_bf16 v[44:47], v[132:135], v[200:203], v[44:47]
	v_mfma_f32_16x16x32_bf16 v[40:43], v[154:157], v[200:203], v[40:43]
	v_mfma_f32_16x16x32_bf16 v[28:31], v[132:135], v[208:211], v[28:31]
	v_mfma_f32_16x16x32_bf16 v[24:27], v[154:157], v[208:211], v[24:27]
	v_mfma_f32_16x16x32_bf16 v[12:15], v[132:135], v[216:219], v[12:15]
	v_mfma_f32_16x16x32_bf16 v[8:11], v[154:157], v[216:219], v[8:11]
	s_setprio 0
	s_setprio 1
	v_mfma_f32_16x16x32_bf16 v[52:55], v[158:161], v[174:177], v[52:55]
	v_mfma_f32_16x16x32_bf16 v[48:51], v[166:169], v[174:177], v[48:51]
	v_mfma_f32_16x16x32_bf16 v[36:39], v[158:161], v[182:185], v[36:39]
	v_mfma_f32_16x16x32_bf16 v[32:35], v[166:169], v[182:185], v[32:35]
	v_mfma_f32_16x16x32_bf16 v[20:23], v[158:161], v[204:207], v[20:23]
	v_mfma_f32_16x16x32_bf16 v[16:19], v[166:169], v[204:207], v[16:19]
	v_mfma_f32_16x16x32_bf16 v[4:7], v[158:161], v[212:215], v[4:7]
	v_mfma_f32_16x16x32_bf16 v[0:3], v[166:169], v[212:215], v[0:3]
	v_mfma_f32_16x16x32_bf16 v[52:55], v[162:165], v[178:181], v[52:55]
	v_mfma_f32_16x16x32_bf16 v[48:51], v[170:173], v[178:181], v[48:51]
	v_mfma_f32_16x16x32_bf16 v[36:39], v[162:165], v[200:203], v[36:39]
	v_mfma_f32_16x16x32_bf16 v[32:35], v[170:173], v[200:203], v[32:35]
	s_add_i32 s61, s61, 2
	s_add_u32 s6, s6, 0x100
	s_addc_u32 s7, s7, 0
	s_add_u32 s59, s59, 0x100
	s_addc_u32 s60, s60, 0
	s_cmp_gt_u32 s61, 13
	v_mfma_f32_16x16x32_bf16 v[20:23], v[162:165], v[208:211], v[20:23]
	v_mfma_f32_16x16x32_bf16 v[16:19], v[170:173], v[208:211], v[16:19]
	v_mfma_f32_16x16x32_bf16 v[4:7], v[162:165], v[216:219], v[4:7]
	v_mfma_f32_16x16x32_bf16 v[0:3], v[170:173], v[216:219], v[0:3]
	s_setprio 0
	s_barrier
	s_cbranch_scc0 .LBB0_484
	s_and_b64 vcc, exec, s[62:63]
	s_cbranch_vccz .LBB0_487
	s_barrier

; #define PG8_STAGE(bufoff, gbase, voff) do { _Pragma("unroll") for (int _i = 0; _i < 2; ++_i) \
;         __builtin_amdgcn_global_load_lds((const unsigned*)((const char*)(gbase) + (voff)[_i]), (PG8_LAS unsigned*)(lds + (bufoff) + ldsw + _i * 8192), 16, 0, 0); } while (0)
; #define PG8_LDA(dst, b, h) do { _Pragma("unroll") for (int m = 0; m < 4; ++m) _Pragma("unroll") for (int k = 0; k < 2; ++k) dst[m][k] = *(const PG8_LAS bf16x8*)(lds + PG8_SA(b, h) + aoff + m * 2048 + k * 1024); } while (0)
; #define PG8_LDB(dst, b, h) do { _Pragma("unroll") for (int n = 0; n < 2; ++n) _Pragma("unroll") for (int k = 0; k < 2; ++k) dst[n][k] = *(const PG8_LAS bf16x8*)(lds + PG8_SB(b, h) + boff + n * 2048 + k * 1024); } while (0)
; #define PG8_MMA(ai, bj, At, Bt) do { __builtin_amdgcn_s_setprio(1); _Pragma("unroll") for (int m = 0; m < 4; ++m) _Pragma("unroll") for (int n = 0; n < 2; ++n) _Pragma("unroll") for (int k = 0; k < 2; ++k) \
;         acc[ai][bj][m][n] = __builtin_amdgcn_mfma_f32_16x16x32_bf16(Bt[n][k], At[m][k], acc[ai][bj][m][n], 0, 0, 0); __builtin_amdgcn_s_setprio(0); } while (0)
; #define PG8_WAIT_V(n) asm volatile("s_waitcnt vmcnt(" #n ")" ::: "memory")
; #define PG8_WAIT_L(n) asm volatile("s_waitcnt lgkmcnt(" #n ")" ::: "memory")
; template <class Epi, class Sched, bool ALIGN_EPI = false, bool SP2 = false>
; __device__ __forceinline__ void gemm_phase(PG8_LAS unsigned char* lds, const Gemm g, const Sched S, const Epi E) {
;     ...
;             const bool last = (t == nt - 2);
;             const char* a1 = cA + (size_t)(t + 1) * kstep;
;             const char* a2 = last ? nA : cA + (size_t)(t + 2) * kstep; const char* b2 = last ? nB : cB + (size_t)(t + 2) * kstep;
;             const char* a3 = a2 + kstep; const char* b3 = b2 + kstep;
;             if (last && has_next) S.a_ready(nxt);
;             if constexpr (SP2) {
;             PG8_LDB(B0, 0, 0); PG8_LDB(B1, 0, 1); PG8_SCHED; PG8_LDA(At, 0, 0); PG8_STAGE(PG8_SA(1, 1), a1 + hstep, voffA);
;             PG8_WAIT_V(8); PG8_WAIT_L(0); PG8_BAR; PG8_MMA(0, 0, At, B0); PG8_MMA(0, 1, At, B1); PG8_BAR; PG8_SCHED;
;             PG8_LDA(At, 0, 1); PG8_STAGE(PG8_SB(0, 0), b2, voffB); PG8_STAGE(PG8_SB(0, 1), b2 + hstep, voffB); PG8_STAGE(PG8_SA(0, 0), a2, voffA);
;             PG8_WAIT_V(8); PG8_WAIT_L(0); PG8_BAR; PG8_MMA(1, 0, At, B0); PG8_MMA(1, 1, At, B1); PG8_BAR; PG8_SCHED;
.Lpagefit_6:
.LBB0_1025:
	ds_read_b128 v[152:155], v149
	ds_read_b128 v[156:159], v149 offset:1024
	ds_read_b128 v[160:163], v149 offset:2048
	ds_read_b128 v[164:167], v149 offset:3072
	ds_read_b128 v[168:171], v150
	ds_read_b128 v[172:175], v150 offset:1024
	ds_read_b128 v[176:179], v150 offset:2048
	ds_read_b128 v[180:183], v150 offset:3072
	s_add_u32 s42, s40, 0xfffc0080
	s_addc_u32 s43, s41, -1
	s_cmp_eq_u32 s63, 12
	s_cselect_b32 s45, s19, s43
	s_cselect_b32 s44, s59, s42
	s_cselect_b32 s43, s17, s62
	s_cselect_b32 s42, s60, s61
	v_lshl_add_u64 v[144:145], s[40:41], 0, v[136:137]
	s_add_i32 m0, s12, 0xc000
	ds_read_b128 v[190:193], v151
	ds_read_b128 v[194:197], v151 offset:1024
	ds_read_b128 v[198:201], v151 offset:2048
	ds_read_b128 v[202:205], v151 offset:3072
	ds_read_b128 v[206:209], v151 offset:4096
	ds_read_b128 v[210:213], v151 offset:5120
	ds_read_b128 v[214:217], v151 offset:6144
	ds_read_b128 v[218:221], v151 offset:7168
	global_load_lds_dwordx4 v[144:145], off
	v_lshl_add_u64 v[144:145], s[40:41], 0, v[138:139]
	s_add_i32 m0, s12, 0xe000
	s_nop 0
	global_load_lds_dwordx4 v[144:145], off
	s_waitcnt vmcnt(8)
	s_waitcnt lgkmcnt(0)
	s_barrier
	s_setprio 1
	s_waitcnt lgkmcnt(0)
	v_mfma_f32_16x16x32_bf16 v[124:127], v[152:155], v[190:193], v[124:127]
	v_mfma_f32_16x16x32_bf16 v[116:119], v[160:163], v[190:193], v[116:119]
	v_mfma_f32_16x16x32_bf16 v[108:111], v[152:155], v[198:201], v[108:111]
	v_mfma_f32_16x16x32_bf16 v[100:103], v[160:163], v[198:201], v[100:103]
	v_mfma_f32_16x16x32_bf16 v[92:95], v[152:155], v[206:209], v[92:95]
	v_mfma_f32_16x16x32_bf16 v[84:87], v[160:163], v[206:209], v[84:87]
	v_mfma_f32_16x16x32_bf16 v[76:79], v[152:155], v[214:217], v[76:79]
	v_mfma_f32_16x16x32_bf16 v[68:71], v[160:163], v[214:217], v[68:71]
	v_mfma_f32_16x16x32_bf16 v[124:127], v[156:159], v[194:197], v[124:127]
	v_mfma_f32_16x16x32_bf16 v[116:119], v[164:167], v[194:197], v[116:119]
	v_mfma_f32_16x16x32_bf16 v[108:111], v[156:159], v[202:205], v[108:111]
	v_mfma_f32_16x16x32_bf16 v[100:103], v[164:167], v[202:205], v[100:103]
	v_mfma_f32_16x16x32_bf16 v[92:95], v[156:159], v[210:213], v[92:95]
	v_mfma_f32_16x16x32_bf16 v[84:87], v[164:167], v[210:213], v[84:87]
	v_mfma_f32_16x16x32_bf16 v[76:79], v[156:159], v[218:221], v[76:79]
	v_mfma_f32_16x16x32_bf16 v[68:71], v[164:167], v[218:221], v[68:71]
	s_setprio 0
	s_setprio 1
	v_mfma_f32_16x16x32_bf16 v[120:123], v[168:171], v[190:193], v[120:123]
	v_mfma_f32_16x16x32_bf16 v[112:115], v[176:179], v[190:193], v[112:115]
	v_mfma_f32_16x16x32_bf16 v[104:107], v[168:171], v[198:201], v[104:107]
	v_mfma_f32_16x16x32_bf16 v[96:99], v[176:179], v[198:201], v[96:99]
	v_mfma_f32_16x16x32_bf16 v[88:91], v[168:171], v[206:209], v[88:91]
	v_mfma_f32_16x16x32_bf16 v[80:83], v[176:179], v[206:209], v[80:83]
	v_mfma_f32_16x16x32_bf16 v[72:75], v[168:171], v[214:217], v[72:75]
	v_mfma_f32_16x16x32_bf16 v[64:67], v[176:179], v[214:217], v[64:67]
	v_mfma_f32_16x16x32_bf16 v[120:123], v[172:175], v[194:197], v[120:123]
	v_mfma_f32_16x16x32_bf16 v[112:115], v[180:183], v[194:197], v[112:115]
	v_mfma_f32_16x16x32_bf16 v[104:107], v[172:175], v[202:205], v[104:107]
	v_mfma_f32_16x16x32_bf16 v[96:99], v[180:183], v[202:205], v[96:99]
	v_mfma_f32_16x16x32_bf16 v[88:91], v[172:175], v[210:213], v[88:91]
	v_mfma_f32_16x16x32_bf16 v[80:83], v[180:183], v[210:213], v[80:83]
	v_mfma_f32_16x16x32_bf16 v[72:75], v[172:175], v[218:221], v[72:75]
	v_mfma_f32_16x16x32_bf16 v[64:67], v[180:183], v[218:221], v[64:67]
	s_setprio 0
	s_barrier
	s_add_i32 s64, s53, s8
	v_lshl_add_u64 v[144:145], s[42:43], 0, v[132:133]
	s_mov_b32 m0, s64
	ds_read_b128 v[190:193], v151 offset:16384
	ds_read_b128 v[194:197], v151 offset:17408
	ds_read_b128 v[198:201], v151 offset:18432
	ds_read_b128 v[202:205], v151 offset:19456
	ds_read_b128 v[206:209], v151 offset:20480
	ds_read_b128 v[210:213], v151 offset:21504
	ds_read_b128 v[214:217], v151 offset:22528
	ds_read_b128 v[218:221], v151 offset:23552
	global_load_lds_dwordx4 v[144:145], off
	s_add_i32 m0, s64, 0x2000
	s_add_u32 s64, s42, 0x40000
	v_lshl_add_u64 v[184:185], s[42:43], 0, v[128:129]
	s_addc_u32 s65, s43, 0
	s_add_i32 s66, s54, s8
	global_load_lds_dwordx4 v[184:185], off
	v_lshl_add_u64 v[186:187], s[64:65], 0, v[132:133]
	s_mov_b32 m0, s66
	v_lshl_add_u64 v[222:223], s[44:45], 0, v[130:131]
	global_load_lds_dwordx4 v[186:187], off
	v_lshl_add_u64 v[186:187], s[64:65], 0, v[128:129]
	s_add_i32 m0, s66, 0x2000
	s_nop 0
	global_load_lds_dwordx4 v[186:187], off
	v_lshl_add_u64 v[186:187], s[44:45], 0, v[134:135]
	s_mov_b32 m0, s12
	s_nop 0
	global_load_lds_dwordx4 v[186:187], off
	s_mov_b32 m0, s13
	s_nop 0
	global_load_lds_dwordx4 v[222:223], off
	s_waitcnt vmcnt(8)
	s_waitcnt lgkmcnt(0)
	s_barrier
; #define PG8_STAGE(bufoff, gbase, voff) do { _Pragma("unroll") for (int _i = 0; _i < 2; ++_i) \
;         __builtin_amdgcn_global_load_lds((const unsigned*)((const char*)(gbase) + (voff)[_i]), (PG8_LAS unsigned*)(lds + (bufoff) + ldsw + _i * 8192), 16, 0, 0); } while (0)
; #define PG8_LDA(dst, b, h) do { _Pragma("unroll") for (int m = 0; m < 4; ++m) _Pragma("unroll") for (int k = 0; k < 2; ++k) dst[m][k] = *(const PG8_LAS bf16x8*)(lds + PG8_SA(b, h) + aoff + m * 2048 + k * 1024); } while (0)
; #define PG8_LDB(dst, b, h) do { _Pragma("unroll") for (int n = 0; n < 2; ++n) _Pragma("unroll") for (int k = 0; k < 2; ++k) dst[n][k] = *(const PG8_LAS bf16x8*)(lds + PG8_SB(b, h) + boff + n * 2048 + k * 1024); } while (0)
; #define PG8_MMA(ai, bj, At, Bt) do { __builtin_amdgcn_s_setprio(1); _Pragma("unroll") for (int m = 0; m < 4; ++m) _Pragma("unroll") for (int n = 0; n < 2; ++n) _Pragma("unroll") for (int k = 0; k < 2; ++k) \
;         acc[ai][bj][m][n] = __builtin_amdgcn_mfma_f32_16x16x32_bf16(Bt[n][k], At[m][k], acc[ai][bj][m][n], 0, 0, 0); __builtin_amdgcn_s_setprio(0); } while (0)
; #define PG8_WAIT_V(n) asm volatile("s_waitcnt vmcnt(" #n ")" ::: "memory")
; #define PG8_WAIT_L(n) asm volatile("s_waitcnt lgkmcnt(" #n ")" ::: "memory")
; #define PG8_BAR __builtin_amdgcn_s_barrier()
; #define PG8_SCHED __builtin_amdgcn_sched_barrier(0)
; template <class Epi, class Sched, bool ALIGN_EPI = false, bool SP2 = false>
; __device__ __forceinline__ void gemm_phase(PG8_LAS unsigned char* lds, const Gemm g, const Sched S, const Epi E) {
;     ...
;             PG8_WAIT_V(8); PG8_WAIT_L(0); PG8_BAR; PG8_MMA(1, 0, At, B0); PG8_MMA(1, 1, At, B1); PG8_BAR; PG8_SCHED;
;             PG8_LDB(B0, 1, 0); PG8_LDB(B1, 1, 1); PG8_SCHED; PG8_LDA(At, 1, 0); PG8_STAGE(PG8_SA(0, 1), a2 + hstep, voffA);
;             PG8_WAIT_V(8); PG8_WAIT_L(0); PG8_BAR; PG8_MMA(0, 0, At, B0); PG8_MMA(0, 1, At, B1); PG8_BAR; PG8_SCHED;
	s_setprio 1
	s_waitcnt lgkmcnt(0)
	v_mfma_f32_16x16x32_bf16 v[60:63], v[152:155], v[190:193], v[60:63]
	v_mfma_f32_16x16x32_bf16 v[52:55], v[160:163], v[190:193], v[52:55]
	v_mfma_f32_16x16x32_bf16 v[44:47], v[152:155], v[198:201], v[44:47]
	v_mfma_f32_16x16x32_bf16 v[36:39], v[160:163], v[198:201], v[36:39]
	v_mfma_f32_16x16x32_bf16 v[28:31], v[152:155], v[206:209], v[28:31]
	v_mfma_f32_16x16x32_bf16 v[20:23], v[160:163], v[206:209], v[20:23]
	v_mfma_f32_16x16x32_bf16 v[12:15], v[152:155], v[214:217], v[12:15]
	v_mfma_f32_16x16x32_bf16 v[4:7], v[160:163], v[214:217], v[4:7]
	v_mfma_f32_16x16x32_bf16 v[60:63], v[156:159], v[194:197], v[60:63]
	v_mfma_f32_16x16x32_bf16 v[52:55], v[164:167], v[194:197], v[52:55]
	v_mfma_f32_16x16x32_bf16 v[44:47], v[156:159], v[202:205], v[44:47]
	v_mfma_f32_16x16x32_bf16 v[36:39], v[164:167], v[202:205], v[36:39]
	v_mfma_f32_16x16x32_bf16 v[28:31], v[156:159], v[210:213], v[28:31]
	v_mfma_f32_16x16x32_bf16 v[20:23], v[164:167], v[210:213], v[20:23]
	v_mfma_f32_16x16x32_bf16 v[12:15], v[156:159], v[218:221], v[12:15]
	v_mfma_f32_16x16x32_bf16 v[4:7], v[164:167], v[218:221], v[4:7]
	s_setprio 0
	s_setprio 1
	v_mfma_f32_16x16x32_bf16 v[56:59], v[168:171], v[190:193], v[56:59]
	v_mfma_f32_16x16x32_bf16 v[48:51], v[176:179], v[190:193], v[48:51]
	v_mfma_f32_16x16x32_bf16 v[40:43], v[168:171], v[198:201], v[40:43]
	v_mfma_f32_16x16x32_bf16 v[32:35], v[176:179], v[198:201], v[32:35]
	v_mfma_f32_16x16x32_bf16 v[24:27], v[168:171], v[206:209], v[24:27]
	v_mfma_f32_16x16x32_bf16 v[16:19], v[176:179], v[206:209], v[16:19]
	v_mfma_f32_16x16x32_bf16 v[8:11], v[168:171], v[214:217], v[8:11]
	v_mfma_f32_16x16x32_bf16 v[0:3], v[176:179], v[214:217], v[0:3]
	v_mfma_f32_16x16x32_bf16 v[56:59], v[172:175], v[194:197], v[56:59]
	v_mfma_f32_16x16x32_bf16 v[48:51], v[180:183], v[194:197], v[48:51]
	v_mfma_f32_16x16x32_bf16 v[40:43], v[172:175], v[202:205], v[40:43]
	v_mfma_f32_16x16x32_bf16 v[32:35], v[180:183], v[202:205], v[32:35]
	v_mfma_f32_16x16x32_bf16 v[24:27], v[172:175], v[210:213], v[24:27]
	v_mfma_f32_16x16x32_bf16 v[16:19], v[180:183], v[210:213], v[16:19]
	v_mfma_f32_16x16x32_bf16 v[8:11], v[172:175], v[218:221], v[8:11]
	v_mfma_f32_16x16x32_bf16 v[0:3], v[180:183], v[218:221], v[0:3]
	s_setprio 0
	s_barrier
	s_add_i32 s64, 0, 0x18000
	s_add_i32 s65, 0, 0x1c000
	v_add_u32_e32 v164, s64, v148
	v_add_u32_e32 v180, s65, v148
	ds_read_b128 v[152:155], v164
	ds_read_b128 v[156:159], v164 offset:1024
	ds_read_b128 v[160:163], v164 offset:2048
	ds_read_b128 v[164:167], v164 offset:3072
	ds_read_b128 v[168:171], v180
	ds_read_b128 v[172:175], v180 offset:1024
	ds_read_b128 v[176:179], v180 offset:2048
	ds_read_b128 v[180:183], v180 offset:3072
	s_add_u32 s44, s44, 0x40000
	s_addc_u32 s45, s45, 0
	s_mov_b32 m0, s33
	v_lshl_add_u64 v[224:225], s[44:45], 0, v[134:135]
	ds_read_b128 v[190:193], v151 offset:32768
	ds_read_b128 v[194:197], v151 offset:33792
	ds_read_b128 v[198:201], v151 offset:34816
	ds_read_b128 v[202:205], v151 offset:35840
	ds_read_b128 v[206:209], v151 offset:36864
	ds_read_b128 v[210:213], v151 offset:37888
	ds_read_b128 v[214:217], v151 offset:38912
	ds_read_b128 v[218:221], v151 offset:39936
	global_load_lds_dwordx4 v[224:225], off
	v_lshl_add_u64 v[224:225], s[44:45], 0, v[130:131]
	s_mov_b32 m0, s39
	s_nop 0
	global_load_lds_dwordx4 v[224:225], off
	s_waitcnt vmcnt(8)
	s_waitcnt lgkmcnt(0)
	s_barrier
	s_setprio 1
	s_waitcnt lgkmcnt(0)
	v_mfma_f32_16x16x32_bf16 v[124:127], v[152:155], v[190:193], v[124:127]
	v_mfma_f32_16x16x32_bf16 v[116:119], v[160:163], v[190:193], v[116:119]
	v_mfma_f32_16x16x32_bf16 v[108:111], v[152:155], v[198:201], v[108:111]
	v_mfma_f32_16x16x32_bf16 v[100:103], v[160:163], v[198:201], v[100:103]
	v_mfma_f32_16x16x32_bf16 v[92:95], v[152:155], v[206:209], v[92:95]
	v_mfma_f32_16x16x32_bf16 v[84:87], v[160:163], v[206:209], v[84:87]
	v_mfma_f32_16x16x32_bf16 v[76:79], v[152:155], v[214:217], v[76:79]
	v_mfma_f32_16x16x32_bf16 v[68:71], v[160:163], v[214:217], v[68:71]
	v_mfma_f32_16x16x32_bf16 v[124:127], v[156:159], v[194:197], v[124:127]
	v_mfma_f32_16x16x32_bf16 v[116:119], v[164:167], v[194:197], v[116:119]
	v_mfma_f32_16x16x32_bf16 v[108:111], v[156:159], v[202:205], v[108:111]
	v_mfma_f32_16x16x32_bf16 v[100:103], v[164:167], v[202:205], v[100:103]
	v_mfma_f32_16x16x32_bf16 v[92:95], v[156:159], v[210:213], v[92:95]
	v_mfma_f32_16x16x32_bf16 v[84:87], v[164:167], v[210:213], v[84:87]
	v_mfma_f32_16x16x32_bf16 v[76:79], v[156:159], v[218:221], v[76:79]
	v_mfma_f32_16x16x32_bf16 v[68:71], v[164:167], v[218:221], v[68:71]
	s_setprio 0
	s_setprio 1
	v_mfma_f32_16x16x32_bf16 v[120:123], v[168:171], v[190:193], v[120:123]
	v_mfma_f32_16x16x32_bf16 v[112:115], v[176:179], v[190:193], v[112:115]
	v_mfma_f32_16x16x32_bf16 v[104:107], v[168:171], v[198:201], v[104:107]
	v_mfma_f32_16x16x32_bf16 v[96:99], v[176:179], v[198:201], v[96:99]
	v_mfma_f32_16x16x32_bf16 v[88:91], v[168:171], v[206:209], v[88:91]
	v_mfma_f32_16x16x32_bf16 v[80:83], v[176:179], v[206:209], v[80:83]
	v_mfma_f32_16x16x32_bf16 v[72:75], v[168:171], v[214:217], v[72:75]
	v_mfma_f32_16x16x32_bf16 v[64:67], v[176:179], v[214:217], v[64:67]
	v_mfma_f32_16x16x32_bf16 v[120:123], v[172:175], v[194:197], v[120:123]
	v_mfma_f32_16x16x32_bf16 v[112:115], v[180:183], v[194:197], v[112:115]
	v_mfma_f32_16x16x32_bf16 v[104:107], v[172:175], v[202:205], v[104:107]
	v_mfma_f32_16x16x32_bf16 v[96:99], v[180:183], v[202:205], v[96:99]
	v_mfma_f32_16x16x32_bf16 v[88:91], v[172:175], v[210:213], v[88:91]
	v_mfma_f32_16x16x32_bf16 v[80:83], v[180:183], v[210:213], v[80:83]
	v_mfma_f32_16x16x32_bf16 v[72:75], v[172:175], v[218:221], v[72:75]
	v_mfma_f32_16x16x32_bf16 v[64:67], v[180:183], v[218:221], v[64:67]
	s_setprio 0
	s_barrier
; #define PG8_STAGE(bufoff, gbase, voff) do { _Pragma("unroll") for (int _i = 0; _i < 2; ++_i) \
;         __builtin_amdgcn_global_load_lds((const unsigned*)((const char*)(gbase) + (voff)[_i]), (PG8_LAS unsigned*)(lds + (bufoff) + ldsw + _i * 8192), 16, 0, 0); } while (0)
; #define PG8_LDA(dst, b, h) do { _Pragma("unroll") for (int m = 0; m < 4; ++m) _Pragma("unroll") for (int k = 0; k < 2; ++k) dst[m][k] = *(const PG8_LAS bf16x8*)(lds + PG8_SA(b, h) + aoff + m * 2048 + k * 1024); } while (0)
; #define PG8_MMA(ai, bj, At, Bt) do { __builtin_amdgcn_s_setprio(1); _Pragma("unroll") for (int m = 0; m < 4; ++m) _Pragma("unroll") for (int n = 0; n < 2; ++n) _Pragma("unroll") for (int k = 0; k < 2; ++k) \
;         acc[ai][bj][m][n] = __builtin_amdgcn_mfma_f32_16x16x32_bf16(Bt[n][k], At[m][k], acc[ai][bj][m][n], 0, 0, 0); __builtin_amdgcn_s_setprio(0); } while (0)
; #define PG8_WAIT_V(n) asm volatile("s_waitcnt vmcnt(" #n ")" ::: "memory")
; #define PG8_WAIT_L(n) asm volatile("s_waitcnt lgkmcnt(" #n ")" ::: "memory")
; #define PG8_BAR __builtin_amdgcn_s_barrier()
; #define PG8_SCHED __builtin_amdgcn_sched_barrier(0)
; template <class Epi, class Sched, bool ALIGN_EPI = false, bool SP2 = false>
; __device__ __forceinline__ void gemm_phase(PG8_LAS unsigned char* lds, const Gemm g, const Sched S, const Epi E) {
;     ...
;         for (int t = 0; t < nt; t += 2) {
;             if constexpr (Epi::MIDT >= 0) { if (t == Epi::MIDT) E.mid(acc, cur, wr, fr); }
;             const bool last = (t == nt - 2);
;             const char* a1 = cA + (size_t)(t + 1) * kstep;
;             const char* a2 = last ? nA : cA + (size_t)(t + 2) * kstep; const char* b2 = last ? nB : cB + (size_t)(t + 2) * kstep;
;     ...
;             PG8_LDA(At, 1, 1); PG8_STAGE(PG8_SB(1, 0), b3, voffB); PG8_STAGE(PG8_SB(1, 1), b3 + hstep, voffB); PG8_STAGE(PG8_SA(1, 0), a3, voffA);
;             PG8_WAIT_V(8); PG8_WAIT_L(0); PG8_BAR; PG8_MMA(1, 0, At, B0); PG8_MMA(1, 1, At, B1); PG8_BAR; PG8_SCHED;
	s_add_i32 s44, s64, s8
	v_lshl_add_u64 v[144:145], v[144:145], 0, s[10:11]
	s_mov_b32 m0, s44
	ds_read_b128 v[190:193], v151 offset:49152
	ds_read_b128 v[194:197], v151 offset:50176
	ds_read_b128 v[198:201], v151 offset:51200
	ds_read_b128 v[202:205], v151 offset:52224
	ds_read_b128 v[206:209], v151 offset:53248
	ds_read_b128 v[210:213], v151 offset:54272
	ds_read_b128 v[214:217], v151 offset:55296
	ds_read_b128 v[218:221], v151 offset:56320
	global_load_lds_dwordx4 v[144:145], off
	s_add_i32 m0, s44, 0x2000
	s_add_u32 s42, s42, 0x40080
	v_lshl_add_u64 v[144:145], v[184:185], 0, s[10:11]
	s_addc_u32 s43, s43, 0
	s_add_i32 s44, s65, s8
	global_load_lds_dwordx4 v[144:145], off
	v_lshl_add_u64 v[144:145], s[42:43], 0, v[132:133]
	s_mov_b32 m0, s44
	s_nop 0
	global_load_lds_dwordx4 v[144:145], off
	v_lshl_add_u64 v[144:145], s[42:43], 0, v[128:129]
	s_add_i32 m0, s44, 0x2000
	s_nop 0
	global_load_lds_dwordx4 v[144:145], off
	v_lshl_add_u64 v[144:145], v[186:187], 0, s[10:11]
	s_mov_b32 m0, s49
	s_nop 0
	global_load_lds_dwordx4 v[144:145], off
	v_lshl_add_u64 v[144:145], v[222:223], 0, s[10:11]
	s_mov_b32 m0, s50
	s_nop 0
	global_load_lds_dwordx4 v[144:145], off
	s_waitcnt vmcnt(8)
	s_waitcnt lgkmcnt(0)
	s_barrier
	s_setprio 1
	s_waitcnt lgkmcnt(0)
	v_mfma_f32_16x16x32_bf16 v[60:63], v[152:155], v[190:193], v[60:63]
	v_mfma_f32_16x16x32_bf16 v[52:55], v[160:163], v[190:193], v[52:55]
	v_mfma_f32_16x16x32_bf16 v[44:47], v[152:155], v[198:201], v[44:47]
	v_mfma_f32_16x16x32_bf16 v[36:39], v[160:163], v[198:201], v[36:39]
	v_mfma_f32_16x16x32_bf16 v[28:31], v[152:155], v[206:209], v[28:31]
	v_mfma_f32_16x16x32_bf16 v[20:23], v[160:163], v[206:209], v[20:23]
	v_mfma_f32_16x16x32_bf16 v[12:15], v[152:155], v[214:217], v[12:15]
	v_mfma_f32_16x16x32_bf16 v[4:7], v[160:163], v[214:217], v[4:7]
	v_mfma_f32_16x16x32_bf16 v[60:63], v[156:159], v[194:197], v[60:63]
	v_mfma_f32_16x16x32_bf16 v[52:55], v[164:167], v[194:197], v[52:55]
	v_mfma_f32_16x16x32_bf16 v[44:47], v[156:159], v[202:205], v[44:47]
	v_mfma_f32_16x16x32_bf16 v[36:39], v[164:167], v[202:205], v[36:39]
	v_mfma_f32_16x16x32_bf16 v[28:31], v[156:159], v[210:213], v[28:31]
	v_mfma_f32_16x16x32_bf16 v[20:23], v[164:167], v[210:213], v[20:23]
	v_mfma_f32_16x16x32_bf16 v[12:15], v[156:159], v[218:221], v[12:15]
	v_mfma_f32_16x16x32_bf16 v[4:7], v[164:167], v[218:221], v[4:7]
	s_setprio 0
	s_setprio 1
	v_mfma_f32_16x16x32_bf16 v[56:59], v[168:171], v[190:193], v[56:59]
	v_mfma_f32_16x16x32_bf16 v[48:51], v[176:179], v[190:193], v[48:51]
	v_mfma_f32_16x16x32_bf16 v[40:43], v[168:171], v[198:201], v[40:43]
	v_mfma_f32_16x16x32_bf16 v[32:35], v[176:179], v[198:201], v[32:35]
	v_mfma_f32_16x16x32_bf16 v[24:27], v[168:171], v[206:209], v[24:27]
	v_mfma_f32_16x16x32_bf16 v[16:19], v[176:179], v[206:209], v[16:19]
	v_mfma_f32_16x16x32_bf16 v[8:11], v[168:171], v[214:217], v[8:11]
	v_mfma_f32_16x16x32_bf16 v[0:3], v[176:179], v[214:217], v[0:3]
	v_mfma_f32_16x16x32_bf16 v[56:59], v[172:175], v[194:197], v[56:59]
	v_mfma_f32_16x16x32_bf16 v[48:51], v[180:183], v[194:197], v[48:51]
	v_mfma_f32_16x16x32_bf16 v[40:43], v[172:175], v[202:205], v[40:43]
	v_mfma_f32_16x16x32_bf16 v[32:35], v[180:183], v[202:205], v[32:35]
	s_add_i32 s63, s63, 2
	s_add_u32 s40, s40, 0x100
	s_addc_u32 s41, s41, 0
	s_add_u32 s61, s61, 0x100
	s_addc_u32 s62, s62, 0
	s_cmp_gt_u32 s63, 13
	v_mfma_f32_16x16x32_bf16 v[24:27], v[172:175], v[210:213], v[24:27]
	v_mfma_f32_16x16x32_bf16 v[16:19], v[180:183], v[210:213], v[16:19]
	v_mfma_f32_16x16x32_bf16 v[8:11], v[172:175], v[218:221], v[8:11]
	v_mfma_f32_16x16x32_bf16 v[0:3], v[180:183], v[218:221], v[0:3]
	s_setprio 0
	s_barrier
	s_cbranch_scc0 .LBB0_1025
	s_and_b64 vcc, exec, s[14:15]
	s_cbranch_vccz .LBB0_1028
	s_barrier

; #define PG8_STAGE(bufoff, gbase, voff) do { _Pragma("unroll") for (int _i = 0; _i < 2; ++_i) \
;         __builtin_amdgcn_global_load_lds((const unsigned*)((const char*)(gbase) + (voff)[_i]), (PG8_LAS unsigned*)(lds + (bufoff) + ldsw + _i * 8192), 16, 0, 0); } while (0)
; #define PG8_LDA(dst, b, h) do { _Pragma("unroll") for (int m = 0; m < 4; ++m) _Pragma("unroll") for (int k = 0; k < 2; ++k) dst[m][k] = *(const PG8_LAS bf16x8*)(lds + PG8_SA(b, h) + aoff + m * 2048 + k * 1024); } while (0)
; #define PG8_LDB(dst, b, h) do { _Pragma("unroll") for (int n = 0; n < 2; ++n) _Pragma("unroll") for (int k = 0; k < 2; ++k) dst[n][k] = *(const PG8_LAS bf16x8*)(lds + PG8_SB(b, h) + boff + n * 2048 + k * 1024); } while (0)
; #define PG8_MMA(ai, bj, At, Bt) do { __builtin_amdgcn_s_setprio(1); _Pragma("unroll") for (int m = 0; m < 4; ++m) _Pragma("unroll") for (int n = 0; n < 2; ++n) _Pragma("unroll") for (int k = 0; k < 2; ++k) \
;         acc[ai][bj][m][n] = __builtin_amdgcn_mfma_f32_16x16x32_bf16(Bt[n][k], At[m][k], acc[ai][bj][m][n], 0, 0, 0); __builtin_amdgcn_s_setprio(0); } while (0)
; #define PG8_WAIT_V(n) asm volatile("s_waitcnt vmcnt(" #n ")" ::: "memory")
; #define PG8_WAIT_L(n) asm volatile("s_waitcnt lgkmcnt(" #n ")" ::: "memory")
; template <class Epi, class Sched, bool ALIGN_EPI = false, bool SP2 = false>
; __device__ __forceinline__ void gemm_phase(PG8_LAS unsigned char* lds, const Gemm g, const Sched S, const Epi E) {
;     ...
;             const bool last = (t == nt - 2);
;             const char* a1 = cA + (size_t)(t + 1) * kstep;
;             const char* a2 = last ? nA : cA + (size_t)(t + 2) * kstep; const char* b2 = last ? nB : cB + (size_t)(t + 2) * kstep;
;             const char* a3 = a2 + kstep; const char* b3 = b2 + kstep;
;             if (last && has_next) S.a_ready(nxt);
;             if constexpr (SP2) {
;             PG8_LDB(B0, 0, 0); PG8_LDB(B1, 0, 1); PG8_SCHED; PG8_LDA(At, 0, 0); PG8_STAGE(PG8_SA(1, 1), a1 + hstep, voffA);
;             PG8_WAIT_V(8); PG8_WAIT_L(0); PG8_BAR; PG8_MMA(0, 0, At, B0); PG8_MMA(0, 1, At, B1); PG8_BAR; PG8_SCHED;
;             PG8_LDA(At, 0, 1); PG8_STAGE(PG8_SB(0, 0), b2, voffB); PG8_STAGE(PG8_SB(0, 1), b2 + hstep, voffB); PG8_STAGE(PG8_SA(0, 0), a2, voffA);
;             PG8_WAIT_V(8); PG8_WAIT_L(0); PG8_BAR; PG8_MMA(1, 0, At, B0); PG8_MMA(1, 1, At, B1); PG8_BAR; PG8_SCHED;
.LBB0_1105:
	ds_read_b128 v[128:131], v241
	ds_read_b128 v[132:135], v241 offset:1024
	ds_read_b128 v[136:139], v241 offset:2048
	ds_read_b128 v[140:143], v241 offset:3072
	ds_read_b128 v[144:147], v242
	ds_read_b128 v[148:151], v242 offset:1024
	ds_read_b128 v[152:155], v242 offset:2048
	ds_read_b128 v[156:159], v242 offset:3072
	s_add_u32 s48, s46, 0x100
	s_addc_u32 s49, s47, 0
	s_cmp_eq_u32 s71, 40
	s_cselect_b32 s53, s5, s49
	s_cselect_b32 s52, s4, s48
	s_cselect_b32 s51, s45, s70
	s_cselect_b32 s50, s44, s69
	v_lshl_add_u64 v[210:211], s[46:47], 0, v[198:199]
	s_add_i32 m0, s9, 0xc000
	ds_read_b128 v[160:163], v243
	ds_read_b128 v[164:167], v243 offset:1024
	ds_read_b128 v[168:171], v243 offset:2048
	ds_read_b128 v[172:175], v243 offset:3072
	ds_read_b128 v[176:179], v243 offset:4096
	ds_read_b128 v[180:183], v243 offset:5120
	ds_read_b128 v[184:187], v243 offset:6144
	ds_read_b128 v[206:209], v243 offset:7168
	global_load_lds_dwordx4 v[210:211], off
	v_lshl_add_u64 v[210:211], s[46:47], 0, v[200:201]
	s_add_i32 m0, s9, 0xe000
	s_nop 0
	global_load_lds_dwordx4 v[210:211], off
	s_waitcnt vmcnt(8)
	s_waitcnt lgkmcnt(0)
	s_barrier
	s_setprio 1
	s_waitcnt lgkmcnt(0)
	v_mfma_f32_16x16x32_bf16 v[124:127], v[128:131], v[160:163], v[124:127]
	v_mfma_f32_16x16x32_bf16 v[120:123], v[136:139], v[160:163], v[120:123]
	v_mfma_f32_16x16x32_bf16 v[112:115], v[128:131], v[168:171], v[112:115]
	v_mfma_f32_16x16x32_bf16 v[104:107], v[136:139], v[168:171], v[104:107]
	v_mfma_f32_16x16x32_bf16 v[96:99], v[128:131], v[176:179], v[96:99]
	v_mfma_f32_16x16x32_bf16 v[88:91], v[136:139], v[176:179], v[88:91]
	v_mfma_f32_16x16x32_bf16 v[80:83], v[128:131], v[184:187], v[80:83]
	v_mfma_f32_16x16x32_bf16 v[72:75], v[136:139], v[184:187], v[72:75]
	v_mfma_f32_16x16x32_bf16 v[124:127], v[132:135], v[164:167], v[124:127]
	v_mfma_f32_16x16x32_bf16 v[120:123], v[140:143], v[164:167], v[120:123]
	v_mfma_f32_16x16x32_bf16 v[112:115], v[132:135], v[172:175], v[112:115]
	v_mfma_f32_16x16x32_bf16 v[104:107], v[140:143], v[172:175], v[104:107]
	v_mfma_f32_16x16x32_bf16 v[96:99], v[132:135], v[180:183], v[96:99]
	v_mfma_f32_16x16x32_bf16 v[88:91], v[140:143], v[180:183], v[88:91]
	v_mfma_f32_16x16x32_bf16 v[80:83], v[132:135], v[206:209], v[80:83]
	v_mfma_f32_16x16x32_bf16 v[72:75], v[140:143], v[206:209], v[72:75]
	s_setprio 0
	s_setprio 1
	v_mfma_f32_16x16x32_bf16 v[116:119], v[144:147], v[160:163], v[116:119]
	v_mfma_f32_16x16x32_bf16 v[108:111], v[152:155], v[160:163], v[108:111]
	v_mfma_f32_16x16x32_bf16 v[100:103], v[144:147], v[168:171], v[100:103]
	v_mfma_f32_16x16x32_bf16 v[92:95], v[152:155], v[168:171], v[92:95]
	v_mfma_f32_16x16x32_bf16 v[84:87], v[144:147], v[176:179], v[84:87]
	v_mfma_f32_16x16x32_bf16 v[76:79], v[152:155], v[176:179], v[76:79]
	v_mfma_f32_16x16x32_bf16 v[68:71], v[144:147], v[184:187], v[68:71]
	v_mfma_f32_16x16x32_bf16 v[64:67], v[152:155], v[184:187], v[64:67]
	v_mfma_f32_16x16x32_bf16 v[116:119], v[148:151], v[164:167], v[116:119]
	v_mfma_f32_16x16x32_bf16 v[108:111], v[156:159], v[164:167], v[108:111]
	v_mfma_f32_16x16x32_bf16 v[100:103], v[148:151], v[172:175], v[100:103]
	v_mfma_f32_16x16x32_bf16 v[92:95], v[156:159], v[172:175], v[92:95]
	v_mfma_f32_16x16x32_bf16 v[84:87], v[148:151], v[180:183], v[84:87]
	v_mfma_f32_16x16x32_bf16 v[76:79], v[156:159], v[180:183], v[76:79]
	v_mfma_f32_16x16x32_bf16 v[68:71], v[148:151], v[206:209], v[68:71]
	v_mfma_f32_16x16x32_bf16 v[64:67], v[156:159], v[206:209], v[64:67]
	s_setprio 0
	s_barrier
	s_add_i32 s46, s63, s8
	v_lshl_add_u64 v[210:211], s[50:51], 0, v[192:193]
	s_mov_b32 m0, s46
	ds_read_b128 v[160:163], v243 offset:16384
	ds_read_b128 v[164:167], v243 offset:17408
	ds_read_b128 v[168:171], v243 offset:18432
	ds_read_b128 v[172:175], v243 offset:19456
	ds_read_b128 v[176:179], v243 offset:20480
	ds_read_b128 v[180:183], v243 offset:21504
	ds_read_b128 v[184:187], v243 offset:22528
	ds_read_b128 v[206:209], v243 offset:23552
	global_load_lds_dwordx4 v[210:211], off
	s_add_i32 m0, s46, 0x2000
	s_add_u32 s46, s50, 0xb0000
	v_lshl_add_u64 v[212:213], s[50:51], 0, v[196:197]
	s_addc_u32 s47, s51, 0
	s_add_i32 s72, s64, s8
	global_load_lds_dwordx4 v[212:213], off
	v_lshl_add_u64 v[214:215], s[46:47], 0, v[192:193]
	s_mov_b32 m0, s72
	v_lshl_add_u64 v[216:217], s[52:53], 0, v[194:195]
	global_load_lds_dwordx4 v[214:215], off
	v_lshl_add_u64 v[214:215], s[46:47], 0, v[196:197]
	s_add_i32 m0, s72, 0x2000
	s_nop 0
	global_load_lds_dwordx4 v[214:215], off
	v_lshl_add_u64 v[214:215], s[52:53], 0, v[190:191]
	s_mov_b32 m0, s9
	s_nop 0
	global_load_lds_dwordx4 v[214:215], off
	s_mov_b32 m0, s12
	s_nop 0
	global_load_lds_dwordx4 v[216:217], off
	s_waitcnt vmcnt(8)
	s_waitcnt lgkmcnt(0)
	s_barrier
; #define PG8_STAGE(bufoff, gbase, voff) do { _Pragma("unroll") for (int _i = 0; _i < 2; ++_i) \
;         __builtin_amdgcn_global_load_lds((const unsigned*)((const char*)(gbase) + (voff)[_i]), (PG8_LAS unsigned*)(lds + (bufoff) + ldsw + _i * 8192), 16, 0, 0); } while (0)
; #define PG8_LDA(dst, b, h) do { _Pragma("unroll") for (int m = 0; m < 4; ++m) _Pragma("unroll") for (int k = 0; k < 2; ++k) dst[m][k] = *(const PG8_LAS bf16x8*)(lds + PG8_SA(b, h) + aoff + m * 2048 + k * 1024); } while (0)
; #define PG8_LDB(dst, b, h) do { _Pragma("unroll") for (int n = 0; n < 2; ++n) _Pragma("unroll") for (int k = 0; k < 2; ++k) dst[n][k] = *(const PG8_LAS bf16x8*)(lds + PG8_SB(b, h) + boff + n * 2048 + k * 1024); } while (0)
; #define PG8_MMA(ai, bj, At, Bt) do { __builtin_amdgcn_s_setprio(1); _Pragma("unroll") for (int m = 0; m < 4; ++m) _Pragma("unroll") for (int n = 0; n < 2; ++n) _Pragma("unroll") for (int k = 0; k < 2; ++k) \
;         acc[ai][bj][m][n] = __builtin_amdgcn_mfma_f32_16x16x32_bf16(Bt[n][k], At[m][k], acc[ai][bj][m][n], 0, 0, 0); __builtin_amdgcn_s_setprio(0); } while (0)
; #define PG8_WAIT_V(n) asm volatile("s_waitcnt vmcnt(" #n ")" ::: "memory")
; #define PG8_WAIT_L(n) asm volatile("s_waitcnt lgkmcnt(" #n ")" ::: "memory")
; #define PG8_BAR __builtin_amdgcn_s_barrier()
; #define PG8_SCHED __builtin_amdgcn_sched_barrier(0)
; template <class Epi, class Sched, bool ALIGN_EPI = false, bool SP2 = false>
; __device__ __forceinline__ void gemm_phase(PG8_LAS unsigned char* lds, const Gemm g, const Sched S, const Epi E) {
;     ...
;             PG8_WAIT_V(8); PG8_WAIT_L(0); PG8_BAR; PG8_MMA(1, 0, At, B0); PG8_MMA(1, 1, At, B1); PG8_BAR; PG8_SCHED;
;             PG8_LDB(B0, 1, 0); PG8_LDB(B1, 1, 1); PG8_SCHED; PG8_LDA(At, 1, 0); PG8_STAGE(PG8_SA(0, 1), a2 + hstep, voffA);
;             PG8_WAIT_V(8); PG8_WAIT_L(0); PG8_BAR; PG8_MMA(0, 0, At, B0); PG8_MMA(0, 1, At, B1); PG8_BAR; PG8_SCHED;
	s_setprio 1
	s_waitcnt lgkmcnt(0)
	v_mfma_f32_16x16x32_bf16 v[60:63], v[128:131], v[160:163], v[60:63]
	v_mfma_f32_16x16x32_bf16 v[56:59], v[136:139], v[160:163], v[56:59]
	v_mfma_f32_16x16x32_bf16 v[48:51], v[128:131], v[168:171], v[48:51]
	v_mfma_f32_16x16x32_bf16 v[40:43], v[136:139], v[168:171], v[40:43]
	v_mfma_f32_16x16x32_bf16 v[32:35], v[128:131], v[176:179], v[32:35]
	v_mfma_f32_16x16x32_bf16 v[24:27], v[136:139], v[176:179], v[24:27]
	v_mfma_f32_16x16x32_bf16 v[16:19], v[128:131], v[184:187], v[16:19]
	v_mfma_f32_16x16x32_bf16 v[8:11], v[136:139], v[184:187], v[8:11]
	v_mfma_f32_16x16x32_bf16 v[60:63], v[132:135], v[164:167], v[60:63]
	v_mfma_f32_16x16x32_bf16 v[56:59], v[140:143], v[164:167], v[56:59]
	v_mfma_f32_16x16x32_bf16 v[48:51], v[132:135], v[172:175], v[48:51]
	v_mfma_f32_16x16x32_bf16 v[40:43], v[140:143], v[172:175], v[40:43]
	v_mfma_f32_16x16x32_bf16 v[32:35], v[132:135], v[180:183], v[32:35]
	v_mfma_f32_16x16x32_bf16 v[24:27], v[140:143], v[180:183], v[24:27]
	v_mfma_f32_16x16x32_bf16 v[16:19], v[132:135], v[206:209], v[16:19]
	v_mfma_f32_16x16x32_bf16 v[8:11], v[140:143], v[206:209], v[8:11]
	s_setprio 0
	s_setprio 1
	v_mfma_f32_16x16x32_bf16 v[52:55], v[144:147], v[160:163], v[52:55]
	v_mfma_f32_16x16x32_bf16 v[44:47], v[152:155], v[160:163], v[44:47]
	v_mfma_f32_16x16x32_bf16 v[36:39], v[144:147], v[168:171], v[36:39]
	v_mfma_f32_16x16x32_bf16 v[28:31], v[152:155], v[168:171], v[28:31]
	v_mfma_f32_16x16x32_bf16 v[20:23], v[144:147], v[176:179], v[20:23]
	v_mfma_f32_16x16x32_bf16 v[12:15], v[152:155], v[176:179], v[12:15]
	v_mfma_f32_16x16x32_bf16 v[4:7], v[144:147], v[184:187], v[4:7]
	v_mfma_f32_16x16x32_bf16 v[0:3], v[152:155], v[184:187], v[0:3]
	v_mfma_f32_16x16x32_bf16 v[52:55], v[148:151], v[164:167], v[52:55]
	v_mfma_f32_16x16x32_bf16 v[44:47], v[156:159], v[164:167], v[44:47]
	v_mfma_f32_16x16x32_bf16 v[36:39], v[148:151], v[172:175], v[36:39]
	v_mfma_f32_16x16x32_bf16 v[28:31], v[156:159], v[172:175], v[28:31]
	v_mfma_f32_16x16x32_bf16 v[20:23], v[148:151], v[180:183], v[20:23]
	v_mfma_f32_16x16x32_bf16 v[12:15], v[156:159], v[180:183], v[12:15]
	v_mfma_f32_16x16x32_bf16 v[4:7], v[148:151], v[206:209], v[4:7]
	v_mfma_f32_16x16x32_bf16 v[0:3], v[156:159], v[206:209], v[0:3]
	s_setprio 0
	s_barrier
	s_add_i32 s72, 0, 0x18000
	s_add_i32 s73, 0, 0x1c000
	v_add_u32_e32 v140, s72, v240
	v_add_u32_e32 v156, s73, v240
	ds_read_b128 v[128:131], v140
	ds_read_b128 v[132:135], v140 offset:1024
	ds_read_b128 v[136:139], v140 offset:2048
	ds_read_b128 v[140:143], v140 offset:3072
	ds_read_b128 v[144:147], v156
	ds_read_b128 v[148:151], v156 offset:1024
	ds_read_b128 v[152:155], v156 offset:2048
	ds_read_b128 v[156:159], v156 offset:3072
	s_add_u32 s46, s52, 0xb0000
	s_addc_u32 s47, s53, 0
	s_mov_b32 m0, s13
	v_lshl_add_u64 v[218:219], s[46:47], 0, v[190:191]
	ds_read_b128 v[160:163], v243 offset:32768
	ds_read_b128 v[164:167], v243 offset:33792
	ds_read_b128 v[168:171], v243 offset:34816
	ds_read_b128 v[172:175], v243 offset:35840
	ds_read_b128 v[176:179], v243 offset:36864
	ds_read_b128 v[180:183], v243 offset:37888
	ds_read_b128 v[184:187], v243 offset:38912
	ds_read_b128 v[206:209], v243 offset:39936
	global_load_lds_dwordx4 v[218:219], off
	v_lshl_add_u64 v[218:219], s[46:47], 0, v[194:195]
	s_mov_b32 m0, s33
	s_nop 0
	global_load_lds_dwordx4 v[218:219], off
	s_waitcnt vmcnt(8)
	s_waitcnt lgkmcnt(0)
	s_barrier
	s_setprio 1
	s_waitcnt lgkmcnt(0)
	v_mfma_f32_16x16x32_bf16 v[124:127], v[128:131], v[160:163], v[124:127]
	v_mfma_f32_16x16x32_bf16 v[120:123], v[136:139], v[160:163], v[120:123]
	v_mfma_f32_16x16x32_bf16 v[112:115], v[128:131], v[168:171], v[112:115]
	v_mfma_f32_16x16x32_bf16 v[104:107], v[136:139], v[168:171], v[104:107]
	v_mfma_f32_16x16x32_bf16 v[96:99], v[128:131], v[176:179], v[96:99]
	v_mfma_f32_16x16x32_bf16 v[88:91], v[136:139], v[176:179], v[88:91]
	v_mfma_f32_16x16x32_bf16 v[80:83], v[128:131], v[184:187], v[80:83]
	v_mfma_f32_16x16x32_bf16 v[72:75], v[136:139], v[184:187], v[72:75]
	v_mfma_f32_16x16x32_bf16 v[124:127], v[132:135], v[164:167], v[124:127]
	v_mfma_f32_16x16x32_bf16 v[120:123], v[140:143], v[164:167], v[120:123]
	v_mfma_f32_16x16x32_bf16 v[112:115], v[132:135], v[172:175], v[112:115]
	v_mfma_f32_16x16x32_bf16 v[104:107], v[140:143], v[172:175], v[104:107]
	v_mfma_f32_16x16x32_bf16 v[96:99], v[132:135], v[180:183], v[96:99]
	v_mfma_f32_16x16x32_bf16 v[88:91], v[140:143], v[180:183], v[88:91]
	v_mfma_f32_16x16x32_bf16 v[80:83], v[132:135], v[206:209], v[80:83]
	v_mfma_f32_16x16x32_bf16 v[72:75], v[140:143], v[206:209], v[72:75]
	s_setprio 0
	s_setprio 1
	v_mfma_f32_16x16x32_bf16 v[116:119], v[144:147], v[160:163], v[116:119]
	v_mfma_f32_16x16x32_bf16 v[108:111], v[152:155], v[160:163], v[108:111]
	v_mfma_f32_16x16x32_bf16 v[100:103], v[144:147], v[168:171], v[100:103]
	v_mfma_f32_16x16x32_bf16 v[92:95], v[152:155], v[168:171], v[92:95]
	v_mfma_f32_16x16x32_bf16 v[84:87], v[144:147], v[176:179], v[84:87]
	v_mfma_f32_16x16x32_bf16 v[76:79], v[152:155], v[176:179], v[76:79]
	v_mfma_f32_16x16x32_bf16 v[68:71], v[144:147], v[184:187], v[68:71]
	v_mfma_f32_16x16x32_bf16 v[64:67], v[152:155], v[184:187], v[64:67]
	v_mfma_f32_16x16x32_bf16 v[116:119], v[148:151], v[164:167], v[116:119]
	v_mfma_f32_16x16x32_bf16 v[108:111], v[156:159], v[164:167], v[108:111]
	v_mfma_f32_16x16x32_bf16 v[100:103], v[148:151], v[172:175], v[100:103]
	v_mfma_f32_16x16x32_bf16 v[92:95], v[156:159], v[172:175], v[92:95]
	v_mfma_f32_16x16x32_bf16 v[84:87], v[148:151], v[180:183], v[84:87]
	v_mfma_f32_16x16x32_bf16 v[76:79], v[156:159], v[180:183], v[76:79]
	v_mfma_f32_16x16x32_bf16 v[68:71], v[148:151], v[206:209], v[68:71]
	v_mfma_f32_16x16x32_bf16 v[64:67], v[156:159], v[206:209], v[64:67]
	s_setprio 0
	s_barrier
; #define PG8_STAGE(bufoff, gbase, voff) do { _Pragma("unroll") for (int _i = 0; _i < 2; ++_i) \
;         __builtin_amdgcn_global_load_lds((const unsigned*)((const char*)(gbase) + (voff)[_i]), (PG8_LAS unsigned*)(lds + (bufoff) + ldsw + _i * 8192), 16, 0, 0); } while (0)
; #define PG8_LDA(dst, b, h) do { _Pragma("unroll") for (int m = 0; m < 4; ++m) _Pragma("unroll") for (int k = 0; k < 2; ++k) dst[m][k] = *(const PG8_LAS bf16x8*)(lds + PG8_SA(b, h) + aoff + m * 2048 + k * 1024); } while (0)
; #define PG8_MMA(ai, bj, At, Bt) do { __builtin_amdgcn_s_setprio(1); _Pragma("unroll") for (int m = 0; m < 4; ++m) _Pragma("unroll") for (int n = 0; n < 2; ++n) _Pragma("unroll") for (int k = 0; k < 2; ++k) \
;         acc[ai][bj][m][n] = __builtin_amdgcn_mfma_f32_16x16x32_bf16(Bt[n][k], At[m][k], acc[ai][bj][m][n], 0, 0, 0); __builtin_amdgcn_s_setprio(0); } while (0)
; #define PG8_WAIT_V(n) asm volatile("s_waitcnt vmcnt(" #n ")" ::: "memory")
; #define PG8_WAIT_L(n) asm volatile("s_waitcnt lgkmcnt(" #n ")" ::: "memory")
; #define PG8_BAR __builtin_amdgcn_s_barrier()
; #define PG8_SCHED __builtin_amdgcn_sched_barrier(0)
; template <class Epi, class Sched, bool ALIGN_EPI = false, bool SP2 = false>
; __device__ __forceinline__ void gemm_phase(PG8_LAS unsigned char* lds, const Gemm g, const Sched S, const Epi E) {
;     ...
;         for (int t = 0; t < nt; t += 2) {
;             if constexpr (Epi::MIDT >= 0) { if (t == Epi::MIDT) E.mid(acc, cur, wr, fr); }
;             const bool last = (t == nt - 2);
;             const char* a1 = cA + (size_t)(t + 1) * kstep;
;             const char* a2 = last ? nA : cA + (size_t)(t + 2) * kstep; const char* b2 = last ? nB : cB + (size_t)(t + 2) * kstep;
;     ...
;             PG8_LDA(At, 1, 1); PG8_STAGE(PG8_SB(1, 0), b3, voffB); PG8_STAGE(PG8_SB(1, 1), b3 + hstep, voffB); PG8_STAGE(PG8_SA(1, 0), a3, voffA);
;             PG8_WAIT_V(8); PG8_WAIT_L(0); PG8_BAR; PG8_MMA(1, 0, At, B0); PG8_MMA(1, 1, At, B1); PG8_BAR; PG8_SCHED;
	s_add_i32 s46, s72, s8
	v_lshl_add_u64 v[210:211], v[210:211], 0, s[10:11]
	s_mov_b32 m0, s46
	ds_read_b128 v[160:163], v243 offset:49152
	ds_read_b128 v[164:167], v243 offset:50176
	ds_read_b128 v[168:171], v243 offset:51200
	ds_read_b128 v[172:175], v243 offset:52224
	ds_read_b128 v[176:179], v243 offset:53248
	ds_read_b128 v[180:183], v243 offset:54272
	ds_read_b128 v[184:187], v243 offset:55296
	ds_read_b128 v[206:209], v243 offset:56320
	global_load_lds_dwordx4 v[210:211], off
	s_add_i32 m0, s46, 0x2000
	s_add_u32 s46, s50, 0xb0080
	v_lshl_add_u64 v[210:211], v[212:213], 0, s[10:11]
	s_addc_u32 s47, s51, 0
	s_add_i32 s50, s73, s8
	global_load_lds_dwordx4 v[210:211], off
	v_lshl_add_u64 v[210:211], s[46:47], 0, v[192:193]
	s_mov_b32 m0, s50
	s_nop 0
	global_load_lds_dwordx4 v[210:211], off
	v_lshl_add_u64 v[210:211], s[46:47], 0, v[196:197]
	s_add_i32 m0, s50, 0x2000
	s_nop 0
	global_load_lds_dwordx4 v[210:211], off
	v_lshl_add_u64 v[210:211], v[214:215], 0, s[10:11]
	s_mov_b32 m0, s59
	s_nop 0
	global_load_lds_dwordx4 v[210:211], off
	v_lshl_add_u64 v[210:211], v[216:217], 0, s[10:11]
	s_mov_b32 m0, s60
	s_nop 0
	global_load_lds_dwordx4 v[210:211], off
	s_waitcnt vmcnt(8)
	s_waitcnt lgkmcnt(0)
	s_barrier
	s_setprio 1
	s_waitcnt lgkmcnt(0)
	v_mfma_f32_16x16x32_bf16 v[60:63], v[128:131], v[160:163], v[60:63]
	v_mfma_f32_16x16x32_bf16 v[56:59], v[136:139], v[160:163], v[56:59]
	v_mfma_f32_16x16x32_bf16 v[48:51], v[128:131], v[168:171], v[48:51]
	v_mfma_f32_16x16x32_bf16 v[40:43], v[136:139], v[168:171], v[40:43]
	v_mfma_f32_16x16x32_bf16 v[32:35], v[128:131], v[176:179], v[32:35]
	v_mfma_f32_16x16x32_bf16 v[24:27], v[136:139], v[176:179], v[24:27]
	v_mfma_f32_16x16x32_bf16 v[16:19], v[128:131], v[184:187], v[16:19]
	v_mfma_f32_16x16x32_bf16 v[8:11], v[136:139], v[184:187], v[8:11]
	v_mfma_f32_16x16x32_bf16 v[60:63], v[132:135], v[164:167], v[60:63]
	v_mfma_f32_16x16x32_bf16 v[56:59], v[140:143], v[164:167], v[56:59]
	v_mfma_f32_16x16x32_bf16 v[48:51], v[132:135], v[172:175], v[48:51]
	v_mfma_f32_16x16x32_bf16 v[40:43], v[140:143], v[172:175], v[40:43]
	v_mfma_f32_16x16x32_bf16 v[32:35], v[132:135], v[180:183], v[32:35]
	v_mfma_f32_16x16x32_bf16 v[24:27], v[140:143], v[180:183], v[24:27]
	v_mfma_f32_16x16x32_bf16 v[16:19], v[132:135], v[206:209], v[16:19]
	v_mfma_f32_16x16x32_bf16 v[8:11], v[140:143], v[206:209], v[8:11]
	s_setprio 0
	s_setprio 1
	v_mfma_f32_16x16x32_bf16 v[52:55], v[144:147], v[160:163], v[52:55]
	v_mfma_f32_16x16x32_bf16 v[44:47], v[152:155], v[160:163], v[44:47]
	v_mfma_f32_16x16x32_bf16 v[36:39], v[144:147], v[168:171], v[36:39]
	v_mfma_f32_16x16x32_bf16 v[28:31], v[152:155], v[168:171], v[28:31]
	v_mfma_f32_16x16x32_bf16 v[20:23], v[144:147], v[176:179], v[20:23]
	v_mfma_f32_16x16x32_bf16 v[12:15], v[152:155], v[176:179], v[12:15]
	v_mfma_f32_16x16x32_bf16 v[4:7], v[144:147], v[184:187], v[4:7]
	v_mfma_f32_16x16x32_bf16 v[0:3], v[152:155], v[184:187], v[0:3]
	v_mfma_f32_16x16x32_bf16 v[52:55], v[148:151], v[164:167], v[52:55]
	v_mfma_f32_16x16x32_bf16 v[44:47], v[156:159], v[164:167], v[44:47]
	v_mfma_f32_16x16x32_bf16 v[36:39], v[148:151], v[172:175], v[36:39]
	v_mfma_f32_16x16x32_bf16 v[28:31], v[156:159], v[172:175], v[28:31]
	s_add_i32 s71, s71, 2
	s_add_u32 s69, s69, 0x100
	s_addc_u32 s70, s70, 0
	s_cmp_gt_u32 s71, 41
	s_mov_b64 s[46:47], s[48:49]
	v_mfma_f32_16x16x32_bf16 v[20:23], v[148:151], v[180:183], v[20:23]
	v_mfma_f32_16x16x32_bf16 v[12:15], v[156:159], v[180:183], v[12:15]
	v_mfma_f32_16x16x32_bf16 v[4:7], v[148:151], v[206:209], v[4:7]
	v_mfma_f32_16x16x32_bf16 v[0:3], v[156:159], v[206:209], v[0:3]
	s_setprio 0
	s_barrier
	s_cbranch_scc0 .LBB0_1105
	s_and_b64 vcc, exec, s[16:17]
	s_cbranch_vccz .LBB0_1108
	s_barrier
